# GEMM K-loops: LDS-DMA m0 hazard slot filled by the address add instead of s_nop 0 (38 sites)
# speedup vs baseline: 1.0034x; 1.0034x over previous
; #define PG8_STAGE(bufoff, gbase, voff) do { _Pragma("unroll") for (int _i = 0; _i < 2; ++_i) \
;         __builtin_amdgcn_global_load_lds((const unsigned*)((const char*)(gbase) + (voff)[_i]), (LAS unsigned*)(lds + (bufoff) + ldsw + _i * 8192), 16, 0, 0); } while (0)
; #define PG8_LDA(dst, b, h) do { _Pragma("unroll") for (int m = 0; m < 4; ++m) _Pragma("unroll") for (int k = 0; k < 2; ++k) dst[m][k] = *(const LAS bf16x8*)(lds + PG8_SA(b, h) + aoff + m * 2048 + k * 1024); } while (0)
; #define PG8_LDB(dst, b, h) do { _Pragma("unroll") for (int n = 0; n < 2; ++n) _Pragma("unroll") for (int k = 0; k < 2; ++k) dst[n][k] = *(const LAS bf16x8*)(lds + PG8_SB(b, h) + boff + n * 2048 + k * 1024); } while (0)
; #define PG8_MMA(ai, bj, At, Bt) do { __builtin_amdgcn_s_setprio(1); _Pragma("unroll") for (int m = 0; m < 4; ++m) _Pragma("unroll") for (int n = 0; n < 2; ++n) _Pragma("unroll") for (int k = 0; k < 2; ++k) \
;         acc[ai][bj][m][n] = __builtin_amdgcn_mfma_f32_16x16x32_bf16(Bt[n][k], At[m][k], acc[ai][bj][m][n], 0, 0, 0); __builtin_amdgcn_s_setprio(0); } while (0)
; #define PG8_WAIT_V(n) asm volatile("s_waitcnt vmcnt(" #n ")" ::: "memory")
; #define PG8_WAIT_L(n) asm volatile("s_waitcnt lgkmcnt(" #n ")" ::: "memory")
; #define PG8_BAR __builtin_amdgcn_s_barrier()
; #define PG8_SCHED __builtin_amdgcn_sched_barrier(0)
; template <class Epi, bool ALIGN_EPI = true, bool SP2 = true>
; DI void gemm_phase(LAS unsigned char* lds, const Gemm g, const StaticOrder& S, const Epi& E) {
;     ...
;             PG8_LDB(B0, 0, 0); PG8_LDB(B1, 0, 1); PG8_SCHED; PG8_LDA(At, 0, 0); PG8_STAGE(PG8_SA(1, 1), a1 + hstepA, voffA);
;             PG8_WAIT_V(8); PG8_WAIT_L(0); PG8_BAR; PG8_MMA(0, 0, At, B0); PG8_MMA(0, 1, At, B1); PG8_BAR; PG8_SCHED;
;             PG8_LDA(At, 0, 1); PG8_STAGE(PG8_SB(0, 0), b2, voffB); PG8_STAGE(PG8_SB(0, 1), b2 + hstepB, voffB); PG8_STAGE(PG8_SA(0, 0), a2, voffA);
;             PG8_WAIT_V(8); PG8_WAIT_L(0); PG8_BAR; PG8_MMA(1, 0, At, B0); PG8_MMA(1, 1, At, B1); PG8_BAR; PG8_SCHED;
.LBB0_261:
	ds_read_b128 v[150:153], v147
	ds_read_b128 v[154:157], v147 offset:1024
	ds_read_b128 v[158:161], v147 offset:2048
	ds_read_b128 v[162:165], v147 offset:3072
	ds_read_b128 v[166:169], v148
	ds_read_b128 v[170:173], v148 offset:1024
	ds_read_b128 v[174:177], v148 offset:2048
	ds_read_b128 v[178:181], v148 offset:3072
	s_add_u32 s46, s34, 0xfff00080
	s_addc_u32 s47, s35, -1
	s_cmp_eq_u32 s78, 60
	s_cselect_b32 s49, s25, s47
	s_cselect_b32 s48, s74, s46
	s_cselect_b32 s47, s23, s77
	s_cselect_b32 s46, s75, s76
	v_lshl_add_u64 v[216:217], s[34:35], 0, v[136:137]
	s_add_i32 m0, s21, 0xc000
	ds_read_b128 v[182:185], v149
	ds_read_b128 v[186:189], v149 offset:1024
	ds_read_b128 v[192:195], v149 offset:2048
	ds_read_b128 v[196:199], v149 offset:3072
	ds_read_b128 v[200:203], v149 offset:4096
	ds_read_b128 v[204:207], v149 offset:5120
	ds_read_b128 v[208:211], v149 offset:6144
	ds_read_b128 v[212:215], v149 offset:7168
	global_load_lds_dwordx4 v[216:217], off
	s_add_i32 m0, s21, 0xe000
	v_lshl_add_u64 v[216:217], s[34:35], 0, v[138:139]
	global_load_lds_dwordx4 v[216:217], off
	s_waitcnt vmcnt(8)
	s_waitcnt lgkmcnt(0)
	s_barrier
	s_waitcnt lgkmcnt(0)
	v_mfma_f32_16x16x32_bf16 v[124:127], v[150:153], v[182:185], v[124:127]
	v_mfma_f32_16x16x32_bf16 v[120:123], v[158:161], v[182:185], v[120:123]
	v_mfma_f32_16x16x32_bf16 v[116:119], v[150:153], v[192:195], v[116:119]
	v_mfma_f32_16x16x32_bf16 v[112:115], v[158:161], v[192:195], v[112:115]
	v_mfma_f32_16x16x32_bf16 v[100:103], v[150:153], v[200:203], v[100:103]
	v_mfma_f32_16x16x32_bf16 v[96:99], v[158:161], v[200:203], v[96:99]
	v_mfma_f32_16x16x32_bf16 v[84:87], v[150:153], v[208:211], v[84:87]
	v_mfma_f32_16x16x32_bf16 v[80:83], v[158:161], v[208:211], v[80:83]
	v_mfma_f32_16x16x32_bf16 v[124:127], v[154:157], v[186:189], v[124:127]
	v_mfma_f32_16x16x32_bf16 v[120:123], v[162:165], v[186:189], v[120:123]
	v_mfma_f32_16x16x32_bf16 v[116:119], v[154:157], v[196:199], v[116:119]
	v_mfma_f32_16x16x32_bf16 v[112:115], v[162:165], v[196:199], v[112:115]
	v_mfma_f32_16x16x32_bf16 v[100:103], v[154:157], v[204:207], v[100:103]
	v_mfma_f32_16x16x32_bf16 v[96:99], v[162:165], v[204:207], v[96:99]
	v_mfma_f32_16x16x32_bf16 v[84:87], v[154:157], v[212:215], v[84:87]
	v_mfma_f32_16x16x32_bf16 v[80:83], v[162:165], v[212:215], v[80:83]
	v_mfma_f32_16x16x32_bf16 v[108:111], v[166:169], v[182:185], v[108:111]
	v_mfma_f32_16x16x32_bf16 v[104:107], v[174:177], v[182:185], v[104:107]
	v_mfma_f32_16x16x32_bf16 v[92:95], v[166:169], v[192:195], v[92:95]
	v_mfma_f32_16x16x32_bf16 v[88:91], v[174:177], v[192:195], v[88:91]
	v_mfma_f32_16x16x32_bf16 v[76:79], v[166:169], v[200:203], v[76:79]
	v_mfma_f32_16x16x32_bf16 v[72:75], v[174:177], v[200:203], v[72:75]
	v_mfma_f32_16x16x32_bf16 v[68:71], v[166:169], v[208:211], v[68:71]
	v_mfma_f32_16x16x32_bf16 v[64:67], v[174:177], v[208:211], v[64:67]
	v_mfma_f32_16x16x32_bf16 v[108:111], v[170:173], v[186:189], v[108:111]
	v_mfma_f32_16x16x32_bf16 v[104:107], v[178:181], v[186:189], v[104:107]
	v_mfma_f32_16x16x32_bf16 v[92:95], v[170:173], v[196:199], v[92:95]
	v_mfma_f32_16x16x32_bf16 v[88:91], v[178:181], v[196:199], v[88:91]
	v_mfma_f32_16x16x32_bf16 v[76:79], v[170:173], v[204:207], v[76:79]
	v_mfma_f32_16x16x32_bf16 v[72:75], v[178:181], v[204:207], v[72:75]
	v_mfma_f32_16x16x32_bf16 v[68:71], v[170:173], v[212:215], v[68:71]
	v_mfma_f32_16x16x32_bf16 v[64:67], v[178:181], v[212:215], v[64:67]
	s_barrier
	s_add_i32 s79, s70, s51
	v_lshl_add_u64 v[216:217], s[46:47], 0, v[132:133]
	s_mov_b32 m0, s79
	ds_read_b128 v[182:185], v149 offset:16384
	ds_read_b128 v[186:189], v149 offset:17408
	ds_read_b128 v[192:195], v149 offset:18432
	ds_read_b128 v[196:199], v149 offset:19456
	ds_read_b128 v[200:203], v149 offset:20480
	ds_read_b128 v[204:207], v149 offset:21504
	ds_read_b128 v[208:211], v149 offset:22528
	ds_read_b128 v[212:215], v149 offset:23552
	global_load_lds_dwordx4 v[216:217], off
	s_add_i32 m0, s79, 0x2000
	s_add_u32 s80, s46, 0x100000
	v_lshl_add_u64 v[218:219], s[46:47], 0, v[128:129]
	s_addc_u32 s81, s47, 0
	s_add_i32 s79, s71, s51
	global_load_lds_dwordx4 v[218:219], off
	v_lshl_add_u64 v[220:221], s[80:81], 0, v[132:133]
	s_mov_b32 m0, s79
	v_lshl_add_u64 v[222:223], s[48:49], 0, v[130:131]
	global_load_lds_dwordx4 v[220:221], off
	s_add_i32 m0, s79, 0x2000
	v_lshl_add_u64 v[220:221], s[80:81], 0, v[128:129]
	global_load_lds_dwordx4 v[220:221], off
	s_mov_b32 m0, s21
	v_lshl_add_u64 v[220:221], s[48:49], 0, v[134:135]
	global_load_lds_dwordx4 v[220:221], off
	s_mov_b32 m0, s62
	s_nop 0
	global_load_lds_dwordx4 v[222:223], off
	s_waitcnt vmcnt(8)
	s_waitcnt lgkmcnt(0)
	s_barrier
; #define PG8_STAGE(bufoff, gbase, voff) do { _Pragma("unroll") for (int _i = 0; _i < 2; ++_i) \
;         __builtin_amdgcn_global_load_lds((const unsigned*)((const char*)(gbase) + (voff)[_i]), (LAS unsigned*)(lds + (bufoff) + ldsw + _i * 8192), 16, 0, 0); } while (0)
; #define PG8_LDA(dst, b, h) do { _Pragma("unroll") for (int m = 0; m < 4; ++m) _Pragma("unroll") for (int k = 0; k < 2; ++k) dst[m][k] = *(const LAS bf16x8*)(lds + PG8_SA(b, h) + aoff + m * 2048 + k * 1024); } while (0)
; #define PG8_LDB(dst, b, h) do { _Pragma("unroll") for (int n = 0; n < 2; ++n) _Pragma("unroll") for (int k = 0; k < 2; ++k) dst[n][k] = *(const LAS bf16x8*)(lds + PG8_SB(b, h) + boff + n * 2048 + k * 1024); } while (0)
; #define PG8_MMA(ai, bj, At, Bt) do { __builtin_amdgcn_s_setprio(1); _Pragma("unroll") for (int m = 0; m < 4; ++m) _Pragma("unroll") for (int n = 0; n < 2; ++n) _Pragma("unroll") for (int k = 0; k < 2; ++k) \
;         acc[ai][bj][m][n] = __builtin_amdgcn_mfma_f32_16x16x32_bf16(Bt[n][k], At[m][k], acc[ai][bj][m][n], 0, 0, 0); __builtin_amdgcn_s_setprio(0); } while (0)
; #define PG8_WAIT_V(n) asm volatile("s_waitcnt vmcnt(" #n ")" ::: "memory")
; #define PG8_WAIT_L(n) asm volatile("s_waitcnt lgkmcnt(" #n ")" ::: "memory")
; #define PG8_BAR __builtin_amdgcn_s_barrier()
; #define PG8_SCHED __builtin_amdgcn_sched_barrier(0)
; template <class Epi, bool ALIGN_EPI = true, bool SP2 = true>
; DI void gemm_phase(LAS unsigned char* lds, const Gemm g, const StaticOrder& S, const Epi& E) {
;     ...
;             PG8_WAIT_V(8); PG8_WAIT_L(0); PG8_BAR; PG8_MMA(1, 0, At, B0); PG8_MMA(1, 1, At, B1); PG8_BAR; PG8_SCHED;
;             PG8_LDB(B0, 1, 0); PG8_LDB(B1, 1, 1); PG8_SCHED; PG8_LDA(At, 1, 0); PG8_STAGE(PG8_SA(0, 1), a2 + hstepA, voffA);
;             PG8_WAIT_V(8); PG8_WAIT_L(0); PG8_BAR; PG8_MMA(0, 0, At, B0); PG8_MMA(0, 1, At, B1); PG8_BAR; PG8_SCHED;
	s_waitcnt lgkmcnt(0)
	v_mfma_f32_16x16x32_bf16 v[60:63], v[150:153], v[182:185], v[60:63]
	v_mfma_f32_16x16x32_bf16 v[56:59], v[158:161], v[182:185], v[56:59]
	v_mfma_f32_16x16x32_bf16 v[52:55], v[150:153], v[192:195], v[52:55]
	v_mfma_f32_16x16x32_bf16 v[48:51], v[158:161], v[192:195], v[48:51]
	v_mfma_f32_16x16x32_bf16 v[36:39], v[150:153], v[200:203], v[36:39]
	v_mfma_f32_16x16x32_bf16 v[32:35], v[158:161], v[200:203], v[32:35]
	v_mfma_f32_16x16x32_bf16 v[20:23], v[150:153], v[208:211], v[20:23]
	v_mfma_f32_16x16x32_bf16 v[16:19], v[158:161], v[208:211], v[16:19]
	v_mfma_f32_16x16x32_bf16 v[60:63], v[154:157], v[186:189], v[60:63]
	v_mfma_f32_16x16x32_bf16 v[56:59], v[162:165], v[186:189], v[56:59]
	v_mfma_f32_16x16x32_bf16 v[52:55], v[154:157], v[196:199], v[52:55]
	v_mfma_f32_16x16x32_bf16 v[48:51], v[162:165], v[196:199], v[48:51]
	v_mfma_f32_16x16x32_bf16 v[36:39], v[154:157], v[204:207], v[36:39]
	v_mfma_f32_16x16x32_bf16 v[32:35], v[162:165], v[204:207], v[32:35]
	v_mfma_f32_16x16x32_bf16 v[20:23], v[154:157], v[212:215], v[20:23]
	v_mfma_f32_16x16x32_bf16 v[16:19], v[162:165], v[212:215], v[16:19]
	v_mfma_f32_16x16x32_bf16 v[44:47], v[166:169], v[182:185], v[44:47]
	v_mfma_f32_16x16x32_bf16 v[40:43], v[174:177], v[182:185], v[40:43]
	v_mfma_f32_16x16x32_bf16 v[28:31], v[166:169], v[192:195], v[28:31]
	v_mfma_f32_16x16x32_bf16 v[24:27], v[174:177], v[192:195], v[24:27]
	v_mfma_f32_16x16x32_bf16 v[12:15], v[166:169], v[200:203], v[12:15]
	v_mfma_f32_16x16x32_bf16 v[8:11], v[174:177], v[200:203], v[8:11]
	v_mfma_f32_16x16x32_bf16 v[4:7], v[166:169], v[208:211], v[4:7]
	v_mfma_f32_16x16x32_bf16 v[0:3], v[174:177], v[208:211], v[0:3]
	v_mfma_f32_16x16x32_bf16 v[44:47], v[170:173], v[186:189], v[44:47]
	v_mfma_f32_16x16x32_bf16 v[40:43], v[178:181], v[186:189], v[40:43]
	v_mfma_f32_16x16x32_bf16 v[28:31], v[170:173], v[196:199], v[28:31]
	v_mfma_f32_16x16x32_bf16 v[24:27], v[178:181], v[196:199], v[24:27]
	v_mfma_f32_16x16x32_bf16 v[12:15], v[170:173], v[204:207], v[12:15]
	v_mfma_f32_16x16x32_bf16 v[8:11], v[178:181], v[204:207], v[8:11]
	v_mfma_f32_16x16x32_bf16 v[4:7], v[170:173], v[212:215], v[4:7]
	v_mfma_f32_16x16x32_bf16 v[0:3], v[178:181], v[212:215], v[0:3]
	s_barrier
	s_add_i32 s79, 0, 0x18000
	s_add_i32 s80, 0, 0x1c000
	v_add_u32_e32 v162, s79, v145
	v_add_u32_e32 v178, s80, v145
	ds_read_b128 v[150:153], v162
	ds_read_b128 v[154:157], v162 offset:1024
	ds_read_b128 v[158:161], v162 offset:2048
	ds_read_b128 v[162:165], v162 offset:3072
	ds_read_b128 v[166:169], v178
	ds_read_b128 v[170:173], v178 offset:1024
	ds_read_b128 v[174:177], v178 offset:2048
	ds_read_b128 v[178:181], v178 offset:3072
	s_add_u32 s48, s48, 0x100000
	s_addc_u32 s49, s49, 0
	s_mov_b32 m0, s63
	v_lshl_add_u64 v[226:227], s[48:49], 0, v[134:135]
	ds_read_b128 v[182:185], v149 offset:32768
	ds_read_b128 v[186:189], v149 offset:33792
	ds_read_b128 v[192:195], v149 offset:34816
	ds_read_b128 v[196:199], v149 offset:35840
	ds_read_b128 v[200:203], v149 offset:36864
	ds_read_b128 v[204:207], v149 offset:37888
	ds_read_b128 v[208:211], v149 offset:38912
	ds_read_b128 v[212:215], v149 offset:39936
	global_load_lds_dwordx4 v[226:227], off
	s_mov_b32 m0, s64
	v_lshl_add_u64 v[226:227], s[48:49], 0, v[130:131]
	global_load_lds_dwordx4 v[226:227], off
	s_waitcnt vmcnt(8)
	s_waitcnt lgkmcnt(0)
	s_barrier
	s_waitcnt lgkmcnt(0)
	v_mfma_f32_16x16x32_bf16 v[124:127], v[150:153], v[182:185], v[124:127]
	v_mfma_f32_16x16x32_bf16 v[120:123], v[158:161], v[182:185], v[120:123]
	v_mfma_f32_16x16x32_bf16 v[116:119], v[150:153], v[192:195], v[116:119]
	v_mfma_f32_16x16x32_bf16 v[112:115], v[158:161], v[192:195], v[112:115]
	v_mfma_f32_16x16x32_bf16 v[100:103], v[150:153], v[200:203], v[100:103]
	v_mfma_f32_16x16x32_bf16 v[96:99], v[158:161], v[200:203], v[96:99]
	v_mfma_f32_16x16x32_bf16 v[84:87], v[150:153], v[208:211], v[84:87]
	v_mfma_f32_16x16x32_bf16 v[80:83], v[158:161], v[208:211], v[80:83]
	v_mfma_f32_16x16x32_bf16 v[124:127], v[154:157], v[186:189], v[124:127]
	v_mfma_f32_16x16x32_bf16 v[120:123], v[162:165], v[186:189], v[120:123]
	v_mfma_f32_16x16x32_bf16 v[116:119], v[154:157], v[196:199], v[116:119]
	v_mfma_f32_16x16x32_bf16 v[112:115], v[162:165], v[196:199], v[112:115]
	v_mfma_f32_16x16x32_bf16 v[100:103], v[154:157], v[204:207], v[100:103]
	v_mfma_f32_16x16x32_bf16 v[96:99], v[162:165], v[204:207], v[96:99]
	v_mfma_f32_16x16x32_bf16 v[84:87], v[154:157], v[212:215], v[84:87]
	v_mfma_f32_16x16x32_bf16 v[80:83], v[162:165], v[212:215], v[80:83]
	v_mfma_f32_16x16x32_bf16 v[108:111], v[166:169], v[182:185], v[108:111]
	v_mfma_f32_16x16x32_bf16 v[104:107], v[174:177], v[182:185], v[104:107]
	v_mfma_f32_16x16x32_bf16 v[92:95], v[166:169], v[192:195], v[92:95]
	v_mfma_f32_16x16x32_bf16 v[88:91], v[174:177], v[192:195], v[88:91]
	v_mfma_f32_16x16x32_bf16 v[76:79], v[166:169], v[200:203], v[76:79]
	v_mfma_f32_16x16x32_bf16 v[72:75], v[174:177], v[200:203], v[72:75]
	v_mfma_f32_16x16x32_bf16 v[68:71], v[166:169], v[208:211], v[68:71]
	v_mfma_f32_16x16x32_bf16 v[64:67], v[174:177], v[208:211], v[64:67]
	v_mfma_f32_16x16x32_bf16 v[108:111], v[170:173], v[186:189], v[108:111]
	v_mfma_f32_16x16x32_bf16 v[104:107], v[178:181], v[186:189], v[104:107]
	v_mfma_f32_16x16x32_bf16 v[92:95], v[170:173], v[196:199], v[92:95]
	v_mfma_f32_16x16x32_bf16 v[88:91], v[178:181], v[196:199], v[88:91]
	v_mfma_f32_16x16x32_bf16 v[76:79], v[170:173], v[204:207], v[76:79]
	v_mfma_f32_16x16x32_bf16 v[72:75], v[178:181], v[204:207], v[72:75]
	v_mfma_f32_16x16x32_bf16 v[68:71], v[170:173], v[212:215], v[68:71]
	v_mfma_f32_16x16x32_bf16 v[64:67], v[178:181], v[212:215], v[64:67]
	s_barrier
; #define PG8_STAGE(bufoff, gbase, voff) do { _Pragma("unroll") for (int _i = 0; _i < 2; ++_i) \
;         __builtin_amdgcn_global_load_lds((const unsigned*)((const char*)(gbase) + (voff)[_i]), (LAS unsigned*)(lds + (bufoff) + ldsw + _i * 8192), 16, 0, 0); } while (0)
; #define PG8_LDA(dst, b, h) do { _Pragma("unroll") for (int m = 0; m < 4; ++m) _Pragma("unroll") for (int k = 0; k < 2; ++k) dst[m][k] = *(const LAS bf16x8*)(lds + PG8_SA(b, h) + aoff + m * 2048 + k * 1024); } while (0)
; #define PG8_MMA(ai, bj, At, Bt) do { __builtin_amdgcn_s_setprio(1); _Pragma("unroll") for (int m = 0; m < 4; ++m) _Pragma("unroll") for (int n = 0; n < 2; ++n) _Pragma("unroll") for (int k = 0; k < 2; ++k) \
;         acc[ai][bj][m][n] = __builtin_amdgcn_mfma_f32_16x16x32_bf16(Bt[n][k], At[m][k], acc[ai][bj][m][n], 0, 0, 0); __builtin_amdgcn_s_setprio(0); } while (0)
; #define PG8_WAIT_V(n) asm volatile("s_waitcnt vmcnt(" #n ")" ::: "memory")
; #define PG8_WAIT_L(n) asm volatile("s_waitcnt lgkmcnt(" #n ")" ::: "memory")
; #define PG8_BAR __builtin_amdgcn_s_barrier()
; #define PG8_SCHED __builtin_amdgcn_sched_barrier(0)
; template <class Epi, bool ALIGN_EPI = true, bool SP2 = true>
; DI void gemm_phase(LAS unsigned char* lds, const Gemm g, const StaticOrder& S, const Epi& E) {
;     ...
;             PG8_LDA(At, 1, 1); PG8_STAGE(PG8_SB(1, 0), b3, voffB); PG8_STAGE(PG8_SB(1, 1), b3 + hstepB, voffB); PG8_STAGE(PG8_SA(1, 0), a3, voffA);
;             PG8_WAIT_V(8); PG8_WAIT_L(0); PG8_BAR; PG8_MMA(1, 0, At, B0); PG8_MMA(1, 1, At, B1); PG8_BAR; PG8_SCHED;
;     ...
;         if constexpr (ALIGN_EPI) { if (wr == 0) PG8_BAR; }
	s_add_i32 s48, s79, s51
	v_lshl_add_u64 v[216:217], v[216:217], 0, s[10:11]
	s_mov_b32 m0, s48
	ds_read_b128 v[182:185], v149 offset:49152
	ds_read_b128 v[186:189], v149 offset:50176
	ds_read_b128 v[192:195], v149 offset:51200
	ds_read_b128 v[196:199], v149 offset:52224
	ds_read_b128 v[200:203], v149 offset:53248
	ds_read_b128 v[204:207], v149 offset:54272
	ds_read_b128 v[208:211], v149 offset:55296
	ds_read_b128 v[212:215], v149 offset:56320
	global_load_lds_dwordx4 v[216:217], off
	s_add_i32 m0, s48, 0x2000
	s_add_u32 s46, s46, 0x100080
	v_lshl_add_u64 v[216:217], v[218:219], 0, s[10:11]
	s_addc_u32 s47, s47, 0
	s_add_i32 s48, s80, s51
	global_load_lds_dwordx4 v[216:217], off
	s_mov_b32 m0, s48
	v_lshl_add_u64 v[216:217], s[46:47], 0, v[132:133]
	global_load_lds_dwordx4 v[216:217], off
	s_add_i32 m0, s48, 0x2000
	v_lshl_add_u64 v[216:217], s[46:47], 0, v[128:129]
	global_load_lds_dwordx4 v[216:217], off
	s_mov_b32 m0, s66
	v_lshl_add_u64 v[216:217], v[220:221], 0, s[10:11]
	global_load_lds_dwordx4 v[216:217], off
	s_mov_b32 m0, s67
	v_lshl_add_u64 v[216:217], v[222:223], 0, s[10:11]
	global_load_lds_dwordx4 v[216:217], off
	s_waitcnt vmcnt(8)
	s_waitcnt lgkmcnt(0)
	s_barrier
	s_waitcnt lgkmcnt(0)
	v_mfma_f32_16x16x32_bf16 v[60:63], v[150:153], v[182:185], v[60:63]
	v_mfma_f32_16x16x32_bf16 v[56:59], v[158:161], v[182:185], v[56:59]
	v_mfma_f32_16x16x32_bf16 v[52:55], v[150:153], v[192:195], v[52:55]
	v_mfma_f32_16x16x32_bf16 v[48:51], v[158:161], v[192:195], v[48:51]
	v_mfma_f32_16x16x32_bf16 v[36:39], v[150:153], v[200:203], v[36:39]
	v_mfma_f32_16x16x32_bf16 v[32:35], v[158:161], v[200:203], v[32:35]
	v_mfma_f32_16x16x32_bf16 v[20:23], v[150:153], v[208:211], v[20:23]
	v_mfma_f32_16x16x32_bf16 v[16:19], v[158:161], v[208:211], v[16:19]
	v_mfma_f32_16x16x32_bf16 v[60:63], v[154:157], v[186:189], v[60:63]
	v_mfma_f32_16x16x32_bf16 v[56:59], v[162:165], v[186:189], v[56:59]
	v_mfma_f32_16x16x32_bf16 v[52:55], v[154:157], v[196:199], v[52:55]
	v_mfma_f32_16x16x32_bf16 v[48:51], v[162:165], v[196:199], v[48:51]
	v_mfma_f32_16x16x32_bf16 v[36:39], v[154:157], v[204:207], v[36:39]
	v_mfma_f32_16x16x32_bf16 v[32:35], v[162:165], v[204:207], v[32:35]
	v_mfma_f32_16x16x32_bf16 v[20:23], v[154:157], v[212:215], v[20:23]
	v_mfma_f32_16x16x32_bf16 v[16:19], v[162:165], v[212:215], v[16:19]
	v_mfma_f32_16x16x32_bf16 v[44:47], v[166:169], v[182:185], v[44:47]
	v_mfma_f32_16x16x32_bf16 v[40:43], v[174:177], v[182:185], v[40:43]
	v_mfma_f32_16x16x32_bf16 v[28:31], v[166:169], v[192:195], v[28:31]
	v_mfma_f32_16x16x32_bf16 v[24:27], v[174:177], v[192:195], v[24:27]
	v_mfma_f32_16x16x32_bf16 v[12:15], v[166:169], v[200:203], v[12:15]
	v_mfma_f32_16x16x32_bf16 v[8:11], v[174:177], v[200:203], v[8:11]
	v_mfma_f32_16x16x32_bf16 v[4:7], v[166:169], v[208:211], v[4:7]
	v_mfma_f32_16x16x32_bf16 v[0:3], v[174:177], v[208:211], v[0:3]
	v_mfma_f32_16x16x32_bf16 v[44:47], v[170:173], v[186:189], v[44:47]
	v_mfma_f32_16x16x32_bf16 v[40:43], v[178:181], v[186:189], v[40:43]
	v_mfma_f32_16x16x32_bf16 v[28:31], v[170:173], v[196:199], v[28:31]
	v_mfma_f32_16x16x32_bf16 v[24:27], v[178:181], v[196:199], v[24:27]
	v_mfma_f32_16x16x32_bf16 v[12:15], v[170:173], v[204:207], v[12:15]
	v_mfma_f32_16x16x32_bf16 v[8:11], v[178:181], v[204:207], v[8:11]
	v_mfma_f32_16x16x32_bf16 v[4:7], v[170:173], v[212:215], v[4:7]
	v_mfma_f32_16x16x32_bf16 v[0:3], v[178:181], v[212:215], v[0:3]
	s_barrier
	s_add_i32 s78, s78, 2
	s_add_u32 s34, s34, 0x100
	s_addc_u32 s35, s35, 0
	s_add_u32 s76, s76, 0x100
	s_addc_u32 s77, s77, 0
	s_cmp_gt_u32 s78, 61
	s_cbranch_scc0 .LBB0_261
	s_and_b64 vcc, exec, s[18:19]
	s_cbranch_vccz .LBB0_264
	s_barrier

; #define PG8_STAGE(bufoff, gbase, voff) do { _Pragma("unroll") for (int _i = 0; _i < 2; ++_i) \
;         __builtin_amdgcn_global_load_lds((const unsigned*)((const char*)(gbase) + (voff)[_i]), (LAS unsigned*)(lds + (bufoff) + ldsw + _i * 8192), 16, 0, 0); } while (0)
; #define PG8_LDA(dst, b, h) do { _Pragma("unroll") for (int m = 0; m < 4; ++m) _Pragma("unroll") for (int k = 0; k < 2; ++k) dst[m][k] = *(const LAS bf16x8*)(lds + PG8_SA(b, h) + aoff + m * 2048 + k * 1024); } while (0)
; #define PG8_LDB(dst, b, h) do { _Pragma("unroll") for (int n = 0; n < 2; ++n) _Pragma("unroll") for (int k = 0; k < 2; ++k) dst[n][k] = *(const LAS bf16x8*)(lds + PG8_SB(b, h) + boff + n * 2048 + k * 1024); } while (0)
; #define PG8_MMA(ai, bj, At, Bt) do { __builtin_amdgcn_s_setprio(1); _Pragma("unroll") for (int m = 0; m < 4; ++m) _Pragma("unroll") for (int n = 0; n < 2; ++n) _Pragma("unroll") for (int k = 0; k < 2; ++k) \
;         acc[ai][bj][m][n] = __builtin_amdgcn_mfma_f32_16x16x32_bf16(Bt[n][k], At[m][k], acc[ai][bj][m][n], 0, 0, 0); __builtin_amdgcn_s_setprio(0); } while (0)
; #define PG8_WAIT_V(n) asm volatile("s_waitcnt vmcnt(" #n ")" ::: "memory")
; #define PG8_WAIT_L(n) asm volatile("s_waitcnt lgkmcnt(" #n ")" ::: "memory")
; template <class Epi, bool ALIGN_EPI = true, bool SP2 = true>
; DI void gemm_phase(LAS unsigned char* lds, const Gemm g, const StaticOrder& S, const Epi& E) {
;     ...
;             const bool last = (t == nt - 2);
;             const char* a1 = cA + (size_t)(t + 1) * kstep;
;             const char* a2 = last ? nA : cA + (size_t)(t + 2) * kstep; const char* b2 = last ? nB : cB + (size_t)(t + 2) * kstep;
;             const char* a3 = a2 + kstep; const char* b3 = b2 + kstep;
;             if (Epi::MID) { if (t == (nt >> 1)) {
;                 if constexpr (ALIGN_EPI) { if (wr == 0) PG8_BAR; }
;                 E.mid(acc, cur, wr, wc, fr, fq);
;                 if constexpr (ALIGN_EPI) { if (wr == 1) PG8_BAR; } } }
;             if constexpr (SP2) {
;             PG8_LDB(B0, 0, 0); PG8_LDB(B1, 0, 1); PG8_SCHED; PG8_LDA(At, 0, 0); PG8_STAGE(PG8_SA(1, 1), a1 + hstepA, voffA);
;             PG8_WAIT_V(8); PG8_WAIT_L(0); PG8_BAR; PG8_MMA(0, 0, At, B0); PG8_MMA(0, 1, At, B1); PG8_BAR; PG8_SCHED;
;             PG8_LDA(At, 0, 1); PG8_STAGE(PG8_SB(0, 0), b2, voffB); PG8_STAGE(PG8_SB(0, 1), b2 + hstepB, voffB); PG8_STAGE(PG8_SA(0, 0), a2, voffA);
.LBB0_334:
	ds_read_b128 v[162:165], v158
	ds_read_b128 v[166:169], v158 offset:1024
	ds_read_b128 v[170:173], v158 offset:2048
	ds_read_b128 v[174:177], v158 offset:3072
	ds_read_b128 v[178:181], v159
	ds_read_b128 v[182:185], v159 offset:1024
	ds_read_b128 v[186:189], v159 offset:2048
	ds_read_b128 v[192:195], v159 offset:3072
	s_add_u32 s30, s0, 0xffb80080
	s_addc_u32 s31, s1, -1
	s_cmp_eq_u32 s76, 12
	s_cselect_b32 s35, s25, s31
	s_cselect_b32 s34, s24, s30
	s_cselect_b32 s31, s23, s75
	s_cselect_b32 s30, s73, s74
	v_lshl_add_u64 v[230:231], s[0:1], 0, v[136:137]
	s_add_i32 m0, s49, 0xc000
	ds_read_b128 v[196:199], v160
	ds_read_b128 v[200:203], v160 offset:1024
	ds_read_b128 v[204:207], v160 offset:2048
	ds_read_b128 v[208:211], v160 offset:3072
	ds_read_b128 v[212:215], v160 offset:4096
	ds_read_b128 v[216:219], v160 offset:5120
	ds_read_b128 v[220:223], v160 offset:6144
	ds_read_b128 v[226:229], v160 offset:7168
	global_load_lds_dwordx4 v[230:231], off
	s_add_i32 m0, s49, 0xe000
	v_lshl_add_u64 v[230:231], s[0:1], 0, v[138:139]
	global_load_lds_dwordx4 v[230:231], off
	s_waitcnt vmcnt(8)
	s_waitcnt lgkmcnt(0)
	s_barrier
	s_waitcnt lgkmcnt(0)
	v_mfma_f32_16x16x32_bf16 v[124:127], v[162:165], v[196:199], v[124:127]
	v_mfma_f32_16x16x32_bf16 v[120:123], v[170:173], v[196:199], v[120:123]
	v_mfma_f32_16x16x32_bf16 v[116:119], v[162:165], v[204:207], v[116:119]
	v_mfma_f32_16x16x32_bf16 v[112:115], v[170:173], v[204:207], v[112:115]
	v_mfma_f32_16x16x32_bf16 v[100:103], v[162:165], v[212:215], v[100:103]
	v_mfma_f32_16x16x32_bf16 v[96:99], v[170:173], v[212:215], v[96:99]
	v_mfma_f32_16x16x32_bf16 v[84:87], v[162:165], v[220:223], v[84:87]
	v_mfma_f32_16x16x32_bf16 v[80:83], v[170:173], v[220:223], v[80:83]
	v_mfma_f32_16x16x32_bf16 v[124:127], v[166:169], v[200:203], v[124:127]
	v_mfma_f32_16x16x32_bf16 v[120:123], v[174:177], v[200:203], v[120:123]
	v_mfma_f32_16x16x32_bf16 v[116:119], v[166:169], v[208:211], v[116:119]
	v_mfma_f32_16x16x32_bf16 v[112:115], v[174:177], v[208:211], v[112:115]
	v_mfma_f32_16x16x32_bf16 v[100:103], v[166:169], v[216:219], v[100:103]
	v_mfma_f32_16x16x32_bf16 v[96:99], v[174:177], v[216:219], v[96:99]
	v_mfma_f32_16x16x32_bf16 v[84:87], v[166:169], v[226:229], v[84:87]
	v_mfma_f32_16x16x32_bf16 v[80:83], v[174:177], v[226:229], v[80:83]
	v_mfma_f32_16x16x32_bf16 v[108:111], v[178:181], v[196:199], v[108:111]
	v_mfma_f32_16x16x32_bf16 v[104:107], v[186:189], v[196:199], v[104:107]
	v_mfma_f32_16x16x32_bf16 v[92:95], v[178:181], v[204:207], v[92:95]
	v_mfma_f32_16x16x32_bf16 v[88:91], v[186:189], v[204:207], v[88:91]
	v_mfma_f32_16x16x32_bf16 v[76:79], v[178:181], v[212:215], v[76:79]
	v_mfma_f32_16x16x32_bf16 v[72:75], v[186:189], v[212:215], v[72:75]
	v_mfma_f32_16x16x32_bf16 v[68:71], v[178:181], v[220:223], v[68:71]
	v_mfma_f32_16x16x32_bf16 v[64:67], v[186:189], v[220:223], v[64:67]
	v_mfma_f32_16x16x32_bf16 v[108:111], v[182:185], v[200:203], v[108:111]
	v_mfma_f32_16x16x32_bf16 v[104:107], v[192:195], v[200:203], v[104:107]
	v_mfma_f32_16x16x32_bf16 v[92:95], v[182:185], v[208:211], v[92:95]
	v_mfma_f32_16x16x32_bf16 v[88:91], v[192:195], v[208:211], v[88:91]
	v_mfma_f32_16x16x32_bf16 v[76:79], v[182:185], v[216:219], v[76:79]
	v_mfma_f32_16x16x32_bf16 v[72:75], v[192:195], v[216:219], v[72:75]
	v_mfma_f32_16x16x32_bf16 v[68:71], v[182:185], v[226:229], v[68:71]
	v_mfma_f32_16x16x32_bf16 v[64:67], v[192:195], v[226:229], v[64:67]
	s_barrier
	s_add_i32 s77, s67, s47
	v_lshl_add_u64 v[230:231], s[30:31], 0, v[134:135]
	s_mov_b32 m0, s77
	ds_read_b128 v[196:199], v160 offset:16384
	ds_read_b128 v[200:203], v160 offset:17408
	ds_read_b128 v[204:207], v160 offset:18432
	ds_read_b128 v[208:211], v160 offset:19456
	ds_read_b128 v[212:215], v160 offset:20480
	ds_read_b128 v[216:219], v160 offset:21504
	ds_read_b128 v[220:223], v160 offset:22528
	ds_read_b128 v[226:229], v160 offset:23552
	global_load_lds_dwordx4 v[230:231], off
	s_add_i32 m0, s77, 0x2000
	s_add_u32 s78, s30, 0x40000
	v_lshl_add_u64 v[232:233], s[30:31], 0, v[132:133]
	s_addc_u32 s79, s31, 0
	s_add_i32 s77, s68, s47
	global_load_lds_dwordx4 v[232:233], off
	v_lshl_add_u64 v[234:235], s[78:79], 0, v[134:135]
	s_mov_b32 m0, s77
	v_lshl_add_u64 v[236:237], s[34:35], 0, v[130:131]
	global_load_lds_dwordx4 v[234:235], off
	s_add_i32 m0, s77, 0x2000
	v_lshl_add_u64 v[234:235], s[78:79], 0, v[132:133]
	global_load_lds_dwordx4 v[234:235], off
	s_mov_b32 m0, s49
	v_lshl_add_u64 v[234:235], s[34:35], 0, v[128:129]
	global_load_lds_dwordx4 v[234:235], off
	s_mov_b32 m0, s50
	s_nop 0
	global_load_lds_dwordx4 v[236:237], off
	s_waitcnt vmcnt(8)
	s_waitcnt lgkmcnt(0)
	s_barrier
; #define PG8_STAGE(bufoff, gbase, voff) do { _Pragma("unroll") for (int _i = 0; _i < 2; ++_i) \
;         __builtin_amdgcn_global_load_lds((const unsigned*)((const char*)(gbase) + (voff)[_i]), (LAS unsigned*)(lds + (bufoff) + ldsw + _i * 8192), 16, 0, 0); } while (0)
; #define PG8_LDA(dst, b, h) do { _Pragma("unroll") for (int m = 0; m < 4; ++m) _Pragma("unroll") for (int k = 0; k < 2; ++k) dst[m][k] = *(const LAS bf16x8*)(lds + PG8_SA(b, h) + aoff + m * 2048 + k * 1024); } while (0)
; #define PG8_LDB(dst, b, h) do { _Pragma("unroll") for (int n = 0; n < 2; ++n) _Pragma("unroll") for (int k = 0; k < 2; ++k) dst[n][k] = *(const LAS bf16x8*)(lds + PG8_SB(b, h) + boff + n * 2048 + k * 1024); } while (0)
; #define PG8_MMA(ai, bj, At, Bt) do { __builtin_amdgcn_s_setprio(1); _Pragma("unroll") for (int m = 0; m < 4; ++m) _Pragma("unroll") for (int n = 0; n < 2; ++n) _Pragma("unroll") for (int k = 0; k < 2; ++k) \
;         acc[ai][bj][m][n] = __builtin_amdgcn_mfma_f32_16x16x32_bf16(Bt[n][k], At[m][k], acc[ai][bj][m][n], 0, 0, 0); __builtin_amdgcn_s_setprio(0); } while (0)
; #define PG8_WAIT_V(n) asm volatile("s_waitcnt vmcnt(" #n ")" ::: "memory")
; #define PG8_WAIT_L(n) asm volatile("s_waitcnt lgkmcnt(" #n ")" ::: "memory")
; #define PG8_BAR __builtin_amdgcn_s_barrier()
; #define PG8_SCHED __builtin_amdgcn_sched_barrier(0)
; template <class Epi, bool ALIGN_EPI = true, bool SP2 = true>
; DI void gemm_phase(LAS unsigned char* lds, const Gemm g, const StaticOrder& S, const Epi& E) {
;     ...
;             PG8_WAIT_V(8); PG8_WAIT_L(0); PG8_BAR; PG8_MMA(1, 0, At, B0); PG8_MMA(1, 1, At, B1); PG8_BAR; PG8_SCHED;
;             PG8_LDB(B0, 1, 0); PG8_LDB(B1, 1, 1); PG8_SCHED; PG8_LDA(At, 1, 0); PG8_STAGE(PG8_SA(0, 1), a2 + hstepA, voffA);
;             PG8_WAIT_V(8); PG8_WAIT_L(0); PG8_BAR; PG8_MMA(0, 0, At, B0); PG8_MMA(0, 1, At, B1); PG8_BAR; PG8_SCHED;
	s_waitcnt lgkmcnt(0)
	v_mfma_f32_16x16x32_bf16 v[60:63], v[162:165], v[196:199], v[60:63]
	v_mfma_f32_16x16x32_bf16 v[56:59], v[170:173], v[196:199], v[56:59]
	v_mfma_f32_16x16x32_bf16 v[52:55], v[162:165], v[204:207], v[52:55]
	v_mfma_f32_16x16x32_bf16 v[48:51], v[170:173], v[204:207], v[48:51]
	v_mfma_f32_16x16x32_bf16 v[36:39], v[162:165], v[212:215], v[36:39]
	v_mfma_f32_16x16x32_bf16 v[32:35], v[170:173], v[212:215], v[32:35]
	v_mfma_f32_16x16x32_bf16 v[20:23], v[162:165], v[220:223], v[20:23]
	v_mfma_f32_16x16x32_bf16 v[16:19], v[170:173], v[220:223], v[16:19]
	v_mfma_f32_16x16x32_bf16 v[60:63], v[166:169], v[200:203], v[60:63]
	v_mfma_f32_16x16x32_bf16 v[56:59], v[174:177], v[200:203], v[56:59]
	v_mfma_f32_16x16x32_bf16 v[52:55], v[166:169], v[208:211], v[52:55]
	v_mfma_f32_16x16x32_bf16 v[48:51], v[174:177], v[208:211], v[48:51]
	v_mfma_f32_16x16x32_bf16 v[36:39], v[166:169], v[216:219], v[36:39]
	v_mfma_f32_16x16x32_bf16 v[32:35], v[174:177], v[216:219], v[32:35]
	v_mfma_f32_16x16x32_bf16 v[20:23], v[166:169], v[226:229], v[20:23]
	v_mfma_f32_16x16x32_bf16 v[16:19], v[174:177], v[226:229], v[16:19]
	v_mfma_f32_16x16x32_bf16 v[44:47], v[178:181], v[196:199], v[44:47]
	v_mfma_f32_16x16x32_bf16 v[40:43], v[186:189], v[196:199], v[40:43]
	v_mfma_f32_16x16x32_bf16 v[28:31], v[178:181], v[204:207], v[28:31]
	v_mfma_f32_16x16x32_bf16 v[24:27], v[186:189], v[204:207], v[24:27]
	v_mfma_f32_16x16x32_bf16 v[12:15], v[178:181], v[212:215], v[12:15]
	v_mfma_f32_16x16x32_bf16 v[8:11], v[186:189], v[212:215], v[8:11]
	v_mfma_f32_16x16x32_bf16 v[4:7], v[178:181], v[220:223], v[4:7]
	v_mfma_f32_16x16x32_bf16 v[0:3], v[186:189], v[220:223], v[0:3]
	v_mfma_f32_16x16x32_bf16 v[44:47], v[182:185], v[200:203], v[44:47]
	v_mfma_f32_16x16x32_bf16 v[40:43], v[192:195], v[200:203], v[40:43]
	v_mfma_f32_16x16x32_bf16 v[28:31], v[182:185], v[208:211], v[28:31]
	v_mfma_f32_16x16x32_bf16 v[24:27], v[192:195], v[208:211], v[24:27]
	v_mfma_f32_16x16x32_bf16 v[12:15], v[182:185], v[216:219], v[12:15]
	v_mfma_f32_16x16x32_bf16 v[8:11], v[192:195], v[216:219], v[8:11]
	v_mfma_f32_16x16x32_bf16 v[4:7], v[182:185], v[226:229], v[4:7]
	v_mfma_f32_16x16x32_bf16 v[0:3], v[192:195], v[226:229], v[0:3]
	s_barrier
	s_add_i32 s77, 0, 0x18000
	v_add_u32_e32 v161, s77, v156
	s_add_i32 s78, 0, 0x1c000
	ds_read_b128 v[162:165], v161
	ds_read_b128 v[166:169], v161 offset:1024
	ds_read_b128 v[170:173], v161 offset:2048
	ds_read_b128 v[174:177], v161 offset:3072
	v_add_u32_e32 v161, s78, v156
	ds_read_b128 v[178:181], v161
	ds_read_b128 v[182:185], v161 offset:1024
	ds_read_b128 v[186:189], v161 offset:2048
	ds_read_b128 v[192:195], v161 offset:3072
	s_add_u32 s34, s34, 0x480000
	s_addc_u32 s35, s35, 0
	s_mov_b32 m0, s51
	v_lshl_add_u64 v[238:239], s[34:35], 0, v[128:129]
	ds_read_b128 v[196:199], v160 offset:32768
	ds_read_b128 v[200:203], v160 offset:33792
	ds_read_b128 v[204:207], v160 offset:34816
	ds_read_b128 v[208:211], v160 offset:35840
	ds_read_b128 v[212:215], v160 offset:36864
	ds_read_b128 v[216:219], v160 offset:37888
	ds_read_b128 v[220:223], v160 offset:38912
	ds_read_b128 v[226:229], v160 offset:39936
	global_load_lds_dwordx4 v[238:239], off
	s_mov_b32 m0, s60
	v_lshl_add_u64 v[238:239], s[34:35], 0, v[130:131]
	global_load_lds_dwordx4 v[238:239], off
	s_waitcnt vmcnt(8)
	s_waitcnt lgkmcnt(0)
	s_barrier
	s_waitcnt lgkmcnt(0)
	v_mfma_f32_16x16x32_bf16 v[124:127], v[162:165], v[196:199], v[124:127]
	v_mfma_f32_16x16x32_bf16 v[120:123], v[170:173], v[196:199], v[120:123]
	v_mfma_f32_16x16x32_bf16 v[116:119], v[162:165], v[204:207], v[116:119]
	v_mfma_f32_16x16x32_bf16 v[112:115], v[170:173], v[204:207], v[112:115]
	v_mfma_f32_16x16x32_bf16 v[100:103], v[162:165], v[212:215], v[100:103]
	v_mfma_f32_16x16x32_bf16 v[96:99], v[170:173], v[212:215], v[96:99]
	v_mfma_f32_16x16x32_bf16 v[84:87], v[162:165], v[220:223], v[84:87]
	v_mfma_f32_16x16x32_bf16 v[80:83], v[170:173], v[220:223], v[80:83]
	v_mfma_f32_16x16x32_bf16 v[124:127], v[166:169], v[200:203], v[124:127]
	v_mfma_f32_16x16x32_bf16 v[120:123], v[174:177], v[200:203], v[120:123]
	v_mfma_f32_16x16x32_bf16 v[116:119], v[166:169], v[208:211], v[116:119]
	v_mfma_f32_16x16x32_bf16 v[112:115], v[174:177], v[208:211], v[112:115]
	v_mfma_f32_16x16x32_bf16 v[100:103], v[166:169], v[216:219], v[100:103]
	v_mfma_f32_16x16x32_bf16 v[96:99], v[174:177], v[216:219], v[96:99]
	v_mfma_f32_16x16x32_bf16 v[84:87], v[166:169], v[226:229], v[84:87]
	v_mfma_f32_16x16x32_bf16 v[80:83], v[174:177], v[226:229], v[80:83]
	v_mfma_f32_16x16x32_bf16 v[108:111], v[178:181], v[196:199], v[108:111]
	v_mfma_f32_16x16x32_bf16 v[104:107], v[186:189], v[196:199], v[104:107]
	v_mfma_f32_16x16x32_bf16 v[92:95], v[178:181], v[204:207], v[92:95]
	v_mfma_f32_16x16x32_bf16 v[88:91], v[186:189], v[204:207], v[88:91]
	v_mfma_f32_16x16x32_bf16 v[76:79], v[178:181], v[212:215], v[76:79]
	v_mfma_f32_16x16x32_bf16 v[72:75], v[186:189], v[212:215], v[72:75]
	v_mfma_f32_16x16x32_bf16 v[68:71], v[178:181], v[220:223], v[68:71]
	v_mfma_f32_16x16x32_bf16 v[64:67], v[186:189], v[220:223], v[64:67]
	v_mfma_f32_16x16x32_bf16 v[108:111], v[182:185], v[200:203], v[108:111]
	v_mfma_f32_16x16x32_bf16 v[104:107], v[192:195], v[200:203], v[104:107]
	v_mfma_f32_16x16x32_bf16 v[92:95], v[182:185], v[208:211], v[92:95]
	v_mfma_f32_16x16x32_bf16 v[88:91], v[192:195], v[208:211], v[88:91]
	v_mfma_f32_16x16x32_bf16 v[76:79], v[182:185], v[216:219], v[76:79]
	v_mfma_f32_16x16x32_bf16 v[72:75], v[192:195], v[216:219], v[72:75]
	v_mfma_f32_16x16x32_bf16 v[68:71], v[182:185], v[226:229], v[68:71]
	v_mfma_f32_16x16x32_bf16 v[64:67], v[192:195], v[226:229], v[64:67]
	s_barrier
; #define PG8_STAGE(bufoff, gbase, voff) do { _Pragma("unroll") for (int _i = 0; _i < 2; ++_i) \
;         __builtin_amdgcn_global_load_lds((const unsigned*)((const char*)(gbase) + (voff)[_i]), (LAS unsigned*)(lds + (bufoff) + ldsw + _i * 8192), 16, 0, 0); } while (0)
; #define PG8_LDA(dst, b, h) do { _Pragma("unroll") for (int m = 0; m < 4; ++m) _Pragma("unroll") for (int k = 0; k < 2; ++k) dst[m][k] = *(const LAS bf16x8*)(lds + PG8_SA(b, h) + aoff + m * 2048 + k * 1024); } while (0)
; #define PG8_MMA(ai, bj, At, Bt) do { __builtin_amdgcn_s_setprio(1); _Pragma("unroll") for (int m = 0; m < 4; ++m) _Pragma("unroll") for (int n = 0; n < 2; ++n) _Pragma("unroll") for (int k = 0; k < 2; ++k) \
;         acc[ai][bj][m][n] = __builtin_amdgcn_mfma_f32_16x16x32_bf16(Bt[n][k], At[m][k], acc[ai][bj][m][n], 0, 0, 0); __builtin_amdgcn_s_setprio(0); } while (0)
; #define PG8_WAIT_V(n) asm volatile("s_waitcnt vmcnt(" #n ")" ::: "memory")
; #define PG8_WAIT_L(n) asm volatile("s_waitcnt lgkmcnt(" #n ")" ::: "memory")
; #define PG8_BAR __builtin_amdgcn_s_barrier()
; #define PG8_SCHED __builtin_amdgcn_sched_barrier(0)
; template <class Epi, bool ALIGN_EPI = true, bool SP2 = true>
; DI void gemm_phase(LAS unsigned char* lds, const Gemm g, const StaticOrder& S, const Epi& E) {
;     ...
;             PG8_LDA(At, 1, 1); PG8_STAGE(PG8_SB(1, 0), b3, voffB); PG8_STAGE(PG8_SB(1, 1), b3 + hstepB, voffB); PG8_STAGE(PG8_SA(1, 0), a3, voffA);
;             PG8_WAIT_V(8); PG8_WAIT_L(0); PG8_BAR; PG8_MMA(1, 0, At, B0); PG8_MMA(1, 1, At, B1); PG8_BAR; PG8_SCHED;
;     ...
;         if constexpr (ALIGN_EPI) { if (wr == 0) PG8_BAR; }
	s_add_i32 s34, s77, s47
	v_lshl_add_u64 v[230:231], v[230:231], 0, s[18:19]
	s_mov_b32 m0, s34
	ds_read_b128 v[196:199], v160 offset:49152
	ds_read_b128 v[200:203], v160 offset:50176
	ds_read_b128 v[204:207], v160 offset:51200
	ds_read_b128 v[208:211], v160 offset:52224
	ds_read_b128 v[212:215], v160 offset:53248
	ds_read_b128 v[216:219], v160 offset:54272
	ds_read_b128 v[220:223], v160 offset:55296
	ds_read_b128 v[226:229], v160 offset:56320
	global_load_lds_dwordx4 v[230:231], off
	s_add_i32 m0, s34, 0x2000
	s_add_u32 s30, s30, 0x40080
	v_lshl_add_u64 v[230:231], v[232:233], 0, s[18:19]
	s_addc_u32 s31, s31, 0
	s_add_i32 s34, s78, s47
	global_load_lds_dwordx4 v[230:231], off
	s_mov_b32 m0, s34
	v_lshl_add_u64 v[230:231], s[30:31], 0, v[134:135]
	global_load_lds_dwordx4 v[230:231], off
	s_add_i32 m0, s34, 0x2000
	v_lshl_add_u64 v[230:231], s[30:31], 0, v[132:133]
	global_load_lds_dwordx4 v[230:231], off
	s_mov_b32 m0, s62
	v_lshl_add_u64 v[230:231], v[234:235], 0, s[18:19]
	global_load_lds_dwordx4 v[230:231], off
	s_mov_b32 m0, s63
	v_lshl_add_u64 v[230:231], v[236:237], 0, s[18:19]
	global_load_lds_dwordx4 v[230:231], off
	s_waitcnt vmcnt(8)
	s_waitcnt lgkmcnt(0)
	s_barrier
	s_waitcnt lgkmcnt(0)
	v_mfma_f32_16x16x32_bf16 v[60:63], v[162:165], v[196:199], v[60:63]
	v_mfma_f32_16x16x32_bf16 v[56:59], v[170:173], v[196:199], v[56:59]
	v_mfma_f32_16x16x32_bf16 v[52:55], v[162:165], v[204:207], v[52:55]
	v_mfma_f32_16x16x32_bf16 v[48:51], v[170:173], v[204:207], v[48:51]
	v_mfma_f32_16x16x32_bf16 v[36:39], v[162:165], v[212:215], v[36:39]
	v_mfma_f32_16x16x32_bf16 v[32:35], v[170:173], v[212:215], v[32:35]
	v_mfma_f32_16x16x32_bf16 v[20:23], v[162:165], v[220:223], v[20:23]
	v_mfma_f32_16x16x32_bf16 v[16:19], v[170:173], v[220:223], v[16:19]
	v_mfma_f32_16x16x32_bf16 v[60:63], v[166:169], v[200:203], v[60:63]
	v_mfma_f32_16x16x32_bf16 v[56:59], v[174:177], v[200:203], v[56:59]
	v_mfma_f32_16x16x32_bf16 v[52:55], v[166:169], v[208:211], v[52:55]
	v_mfma_f32_16x16x32_bf16 v[48:51], v[174:177], v[208:211], v[48:51]
	v_mfma_f32_16x16x32_bf16 v[36:39], v[166:169], v[216:219], v[36:39]
	v_mfma_f32_16x16x32_bf16 v[32:35], v[174:177], v[216:219], v[32:35]
	v_mfma_f32_16x16x32_bf16 v[20:23], v[166:169], v[226:229], v[20:23]
	v_mfma_f32_16x16x32_bf16 v[16:19], v[174:177], v[226:229], v[16:19]
	v_mfma_f32_16x16x32_bf16 v[44:47], v[178:181], v[196:199], v[44:47]
	v_mfma_f32_16x16x32_bf16 v[40:43], v[186:189], v[196:199], v[40:43]
	v_mfma_f32_16x16x32_bf16 v[28:31], v[178:181], v[204:207], v[28:31]
	v_mfma_f32_16x16x32_bf16 v[24:27], v[186:189], v[204:207], v[24:27]
	v_mfma_f32_16x16x32_bf16 v[12:15], v[178:181], v[212:215], v[12:15]
	v_mfma_f32_16x16x32_bf16 v[8:11], v[186:189], v[212:215], v[8:11]
	v_mfma_f32_16x16x32_bf16 v[4:7], v[178:181], v[220:223], v[4:7]
	v_mfma_f32_16x16x32_bf16 v[0:3], v[186:189], v[220:223], v[0:3]
	v_mfma_f32_16x16x32_bf16 v[44:47], v[182:185], v[200:203], v[44:47]
	v_mfma_f32_16x16x32_bf16 v[40:43], v[192:195], v[200:203], v[40:43]
	v_mfma_f32_16x16x32_bf16 v[28:31], v[182:185], v[208:211], v[28:31]
	v_mfma_f32_16x16x32_bf16 v[24:27], v[192:195], v[208:211], v[24:27]
	v_mfma_f32_16x16x32_bf16 v[12:15], v[182:185], v[216:219], v[12:15]
	v_mfma_f32_16x16x32_bf16 v[8:11], v[192:195], v[216:219], v[8:11]
	v_mfma_f32_16x16x32_bf16 v[4:7], v[182:185], v[226:229], v[4:7]
	v_mfma_f32_16x16x32_bf16 v[0:3], v[192:195], v[226:229], v[0:3]
	s_barrier
	s_add_i32 s76, s76, 2
	s_add_u32 s0, s0, 0x100
	s_addc_u32 s1, s1, 0
	s_add_u32 s74, s74, 0x100
	s_addc_u32 s75, s75, 0
	s_cmp_gt_u32 s76, 13
	s_cbranch_scc0 .LBB0_334
	s_and_b64 vcc, exec, s[20:21]
	s_cbranch_vccz .LBB0_337
	s_barrier

; #define PG8_STAGE(bufoff, gbase, voff) do { _Pragma("unroll") for (int _i = 0; _i < 2; ++_i) \
;         __builtin_amdgcn_global_load_lds((const unsigned*)((const char*)(gbase) + (voff)[_i]), (LAS unsigned*)(lds + (bufoff) + ldsw + _i * 8192), 16, 0, 0); } while (0)
; #define PG8_LDA(dst, b, h) do { _Pragma("unroll") for (int m = 0; m < 4; ++m) _Pragma("unroll") for (int k = 0; k < 2; ++k) dst[m][k] = *(const LAS bf16x8*)(lds + PG8_SA(b, h) + aoff + m * 2048 + k * 1024); } while (0)
; #define PG8_LDB(dst, b, h) do { _Pragma("unroll") for (int n = 0; n < 2; ++n) _Pragma("unroll") for (int k = 0; k < 2; ++k) dst[n][k] = *(const LAS bf16x8*)(lds + PG8_SB(b, h) + boff + n * 2048 + k * 1024); } while (0)
; #define PG8_MMA(ai, bj, At, Bt) do { __builtin_amdgcn_s_setprio(1); _Pragma("unroll") for (int m = 0; m < 4; ++m) _Pragma("unroll") for (int n = 0; n < 2; ++n) _Pragma("unroll") for (int k = 0; k < 2; ++k) \
;         acc[ai][bj][m][n] = __builtin_amdgcn_mfma_f32_16x16x32_bf16(Bt[n][k], At[m][k], acc[ai][bj][m][n], 0, 0, 0); __builtin_amdgcn_s_setprio(0); } while (0)
; #define PG8_WAIT_V(n) asm volatile("s_waitcnt vmcnt(" #n ")" ::: "memory")
; #define PG8_WAIT_L(n) asm volatile("s_waitcnt lgkmcnt(" #n ")" ::: "memory")
; template <class Epi, bool ALIGN_EPI = true, bool SP2 = true>
; DI void gemm_phase(LAS unsigned char* lds, const Gemm g, const StaticOrder& S, const Epi& E) {
;     ...
;             const bool last = (t == nt - 2);
;             const char* a1 = cA + (size_t)(t + 1) * kstep;
;             const char* a2 = last ? nA : cA + (size_t)(t + 2) * kstep; const char* b2 = last ? nB : cB + (size_t)(t + 2) * kstep;
;             const char* a3 = a2 + kstep; const char* b3 = b2 + kstep;
;             if (Epi::MID) { if (t == (nt >> 1)) {
;                 if constexpr (ALIGN_EPI) { if (wr == 0) PG8_BAR; }
;                 E.mid(acc, cur, wr, wc, fr, fq);
;                 if constexpr (ALIGN_EPI) { if (wr == 1) PG8_BAR; } } }
;             if constexpr (SP2) {
;             PG8_LDB(B0, 0, 0); PG8_LDB(B1, 0, 1); PG8_SCHED; PG8_LDA(At, 0, 0); PG8_STAGE(PG8_SA(1, 1), a1 + hstepA, voffA);
;             PG8_WAIT_V(8); PG8_WAIT_L(0); PG8_BAR; PG8_MMA(0, 0, At, B0); PG8_MMA(0, 1, At, B1); PG8_BAR; PG8_SCHED;
;             PG8_LDA(At, 0, 1); PG8_STAGE(PG8_SB(0, 0), b2, voffB); PG8_STAGE(PG8_SB(0, 1), b2 + hstepB, voffB); PG8_STAGE(PG8_SA(0, 0), a2, voffA);
.LBB0_360:
	ds_read_b128 v[154:157], v144
	ds_read_b128 v[158:161], v144 offset:1024
	ds_read_b128 v[162:165], v144 offset:2048
	ds_read_b128 v[166:169], v144 offset:3072
	ds_read_b128 v[170:173], v145
	ds_read_b128 v[174:177], v145 offset:1024
	ds_read_b128 v[178:181], v145 offset:2048
	ds_read_b128 v[182:185], v145 offset:3072
	s_add_u32 s60, s0, 0xffb80080
	s_addc_u32 s61, s1, -1
	s_cmp_eq_u32 s90, 4
	s_cselect_b32 s63, s49, s61
	s_cselect_b32 s62, s48, s60
	s_cselect_b32 s61, s47, s89
	s_cselect_b32 s60, s87, s88
	v_lshl_add_u64 v[150:151], s[0:1], 0, v[136:137]
	s_add_i32 m0, s69, 0xc000
	ds_read_b128 v[186:189], v148
	ds_read_b128 v[192:195], v148 offset:1024
	ds_read_b128 v[196:199], v148 offset:2048
	ds_read_b128 v[200:203], v148 offset:3072
	ds_read_b128 v[204:207], v148 offset:4096
	ds_read_b128 v[208:211], v148 offset:5120
	ds_read_b128 v[212:215], v148 offset:6144
	ds_read_b128 v[216:219], v148 offset:7168
	global_load_lds_dwordx4 v[150:151], off
	s_add_i32 m0, s69, 0xe000
	v_lshl_add_u64 v[150:151], s[0:1], 0, v[138:139]
	global_load_lds_dwordx4 v[150:151], off
	s_waitcnt vmcnt(8)
	s_waitcnt lgkmcnt(0)
	s_barrier
	s_waitcnt lgkmcnt(0)
	v_mfma_f32_16x16x32_bf16 v[124:127], v[154:157], v[186:189], v[124:127]
	v_mfma_f32_16x16x32_bf16 v[120:123], v[162:165], v[186:189], v[120:123]
	v_mfma_f32_16x16x32_bf16 v[116:119], v[154:157], v[196:199], v[116:119]
	v_mfma_f32_16x16x32_bf16 v[112:115], v[162:165], v[196:199], v[112:115]
	v_mfma_f32_16x16x32_bf16 v[100:103], v[154:157], v[204:207], v[100:103]
	v_mfma_f32_16x16x32_bf16 v[96:99], v[162:165], v[204:207], v[96:99]
	v_mfma_f32_16x16x32_bf16 v[84:87], v[154:157], v[212:215], v[84:87]
	v_mfma_f32_16x16x32_bf16 v[80:83], v[162:165], v[212:215], v[80:83]
	v_mfma_f32_16x16x32_bf16 v[124:127], v[158:161], v[192:195], v[124:127]
	v_mfma_f32_16x16x32_bf16 v[120:123], v[166:169], v[192:195], v[120:123]
	v_mfma_f32_16x16x32_bf16 v[116:119], v[158:161], v[200:203], v[116:119]
	v_mfma_f32_16x16x32_bf16 v[112:115], v[166:169], v[200:203], v[112:115]
	v_mfma_f32_16x16x32_bf16 v[100:103], v[158:161], v[208:211], v[100:103]
	v_mfma_f32_16x16x32_bf16 v[96:99], v[166:169], v[208:211], v[96:99]
	v_mfma_f32_16x16x32_bf16 v[84:87], v[158:161], v[216:219], v[84:87]
	v_mfma_f32_16x16x32_bf16 v[80:83], v[166:169], v[216:219], v[80:83]
	v_mfma_f32_16x16x32_bf16 v[108:111], v[170:173], v[186:189], v[108:111]
	v_mfma_f32_16x16x32_bf16 v[104:107], v[178:181], v[186:189], v[104:107]
	v_mfma_f32_16x16x32_bf16 v[92:95], v[170:173], v[196:199], v[92:95]
	v_mfma_f32_16x16x32_bf16 v[88:91], v[178:181], v[196:199], v[88:91]
	v_mfma_f32_16x16x32_bf16 v[76:79], v[170:173], v[204:207], v[76:79]
	v_mfma_f32_16x16x32_bf16 v[72:75], v[178:181], v[204:207], v[72:75]
	v_mfma_f32_16x16x32_bf16 v[68:71], v[170:173], v[212:215], v[68:71]
	v_mfma_f32_16x16x32_bf16 v[64:67], v[178:181], v[212:215], v[64:67]
	v_mfma_f32_16x16x32_bf16 v[108:111], v[174:177], v[192:195], v[108:111]
	v_mfma_f32_16x16x32_bf16 v[104:107], v[182:185], v[192:195], v[104:107]
	v_mfma_f32_16x16x32_bf16 v[92:95], v[174:177], v[200:203], v[92:95]
	v_mfma_f32_16x16x32_bf16 v[88:91], v[182:185], v[200:203], v[88:91]
	v_mfma_f32_16x16x32_bf16 v[76:79], v[174:177], v[208:211], v[76:79]
	v_mfma_f32_16x16x32_bf16 v[72:75], v[182:185], v[208:211], v[72:75]
	v_mfma_f32_16x16x32_bf16 v[68:71], v[174:177], v[216:219], v[68:71]
	v_mfma_f32_16x16x32_bf16 v[64:67], v[182:185], v[216:219], v[64:67]
	s_barrier
	s_add_i32 s91, s78, s68
	v_lshl_add_u64 v[150:151], s[60:61], 0, v[132:133]
	s_mov_b32 m0, s91
	ds_read_b128 v[186:189], v148 offset:16384
	ds_read_b128 v[192:195], v148 offset:17408
	ds_read_b128 v[196:199], v148 offset:18432
	ds_read_b128 v[200:203], v148 offset:19456
	ds_read_b128 v[204:207], v148 offset:20480
	ds_read_b128 v[208:211], v148 offset:21504
	ds_read_b128 v[212:215], v148 offset:22528
	ds_read_b128 v[216:219], v148 offset:23552
	global_load_lds_dwordx4 v[150:151], off
	s_add_i32 m0, s91, 0x2000
	s_add_u32 s92, s60, 0x20000
	v_lshl_add_u64 v[220:221], s[60:61], 0, v[134:135]
	s_addc_u32 s93, s61, 0
	s_add_i32 s91, s79, s68
	global_load_lds_dwordx4 v[220:221], off
	v_lshl_add_u64 v[222:223], s[92:93], 0, v[132:133]
	s_mov_b32 m0, s91
	v_lshl_add_u64 v[226:227], s[62:63], 0, v[130:131]
	global_load_lds_dwordx4 v[222:223], off
	s_add_i32 m0, s91, 0x2000
	v_lshl_add_u64 v[222:223], s[92:93], 0, v[134:135]
	global_load_lds_dwordx4 v[222:223], off
	s_mov_b32 m0, s69
	v_lshl_add_u64 v[222:223], s[62:63], 0, v[128:129]
	global_load_lds_dwordx4 v[222:223], off
	s_mov_b32 m0, s70
	s_nop 0
	global_load_lds_dwordx4 v[226:227], off
	s_waitcnt vmcnt(8)
	s_waitcnt lgkmcnt(0)
	s_barrier
; #define PG8_STAGE(bufoff, gbase, voff) do { _Pragma("unroll") for (int _i = 0; _i < 2; ++_i) \
;         __builtin_amdgcn_global_load_lds((const unsigned*)((const char*)(gbase) + (voff)[_i]), (LAS unsigned*)(lds + (bufoff) + ldsw + _i * 8192), 16, 0, 0); } while (0)
; #define PG8_LDA(dst, b, h) do { _Pragma("unroll") for (int m = 0; m < 4; ++m) _Pragma("unroll") for (int k = 0; k < 2; ++k) dst[m][k] = *(const LAS bf16x8*)(lds + PG8_SA(b, h) + aoff + m * 2048 + k * 1024); } while (0)
; #define PG8_LDB(dst, b, h) do { _Pragma("unroll") for (int n = 0; n < 2; ++n) _Pragma("unroll") for (int k = 0; k < 2; ++k) dst[n][k] = *(const LAS bf16x8*)(lds + PG8_SB(b, h) + boff + n * 2048 + k * 1024); } while (0)
; #define PG8_MMA(ai, bj, At, Bt) do { __builtin_amdgcn_s_setprio(1); _Pragma("unroll") for (int m = 0; m < 4; ++m) _Pragma("unroll") for (int n = 0; n < 2; ++n) _Pragma("unroll") for (int k = 0; k < 2; ++k) \
;         acc[ai][bj][m][n] = __builtin_amdgcn_mfma_f32_16x16x32_bf16(Bt[n][k], At[m][k], acc[ai][bj][m][n], 0, 0, 0); __builtin_amdgcn_s_setprio(0); } while (0)
; #define PG8_WAIT_V(n) asm volatile("s_waitcnt vmcnt(" #n ")" ::: "memory")
; #define PG8_WAIT_L(n) asm volatile("s_waitcnt lgkmcnt(" #n ")" ::: "memory")
; #define PG8_BAR __builtin_amdgcn_s_barrier()
; #define PG8_SCHED __builtin_amdgcn_sched_barrier(0)
; template <class Epi, bool ALIGN_EPI = true, bool SP2 = true>
; DI void gemm_phase(LAS unsigned char* lds, const Gemm g, const StaticOrder& S, const Epi& E) {
;     ...
;             PG8_WAIT_V(8); PG8_WAIT_L(0); PG8_BAR; PG8_MMA(1, 0, At, B0); PG8_MMA(1, 1, At, B1); PG8_BAR; PG8_SCHED;
;             PG8_LDB(B0, 1, 0); PG8_LDB(B1, 1, 1); PG8_SCHED; PG8_LDA(At, 1, 0); PG8_STAGE(PG8_SA(0, 1), a2 + hstepA, voffA);
;             PG8_WAIT_V(8); PG8_WAIT_L(0); PG8_BAR; PG8_MMA(0, 0, At, B0); PG8_MMA(0, 1, At, B1); PG8_BAR; PG8_SCHED;
	s_waitcnt lgkmcnt(0)
	v_mfma_f32_16x16x32_bf16 v[60:63], v[154:157], v[186:189], v[60:63]
	v_mfma_f32_16x16x32_bf16 v[56:59], v[162:165], v[186:189], v[56:59]
	v_mfma_f32_16x16x32_bf16 v[52:55], v[154:157], v[196:199], v[52:55]
	v_mfma_f32_16x16x32_bf16 v[48:51], v[162:165], v[196:199], v[48:51]
	v_mfma_f32_16x16x32_bf16 v[36:39], v[154:157], v[204:207], v[36:39]
	v_mfma_f32_16x16x32_bf16 v[32:35], v[162:165], v[204:207], v[32:35]
	v_mfma_f32_16x16x32_bf16 v[20:23], v[154:157], v[212:215], v[20:23]
	v_mfma_f32_16x16x32_bf16 v[16:19], v[162:165], v[212:215], v[16:19]
	v_mfma_f32_16x16x32_bf16 v[60:63], v[158:161], v[192:195], v[60:63]
	v_mfma_f32_16x16x32_bf16 v[56:59], v[166:169], v[192:195], v[56:59]
	v_mfma_f32_16x16x32_bf16 v[52:55], v[158:161], v[200:203], v[52:55]
	v_mfma_f32_16x16x32_bf16 v[48:51], v[166:169], v[200:203], v[48:51]
	v_mfma_f32_16x16x32_bf16 v[36:39], v[158:161], v[208:211], v[36:39]
	v_mfma_f32_16x16x32_bf16 v[32:35], v[166:169], v[208:211], v[32:35]
	v_mfma_f32_16x16x32_bf16 v[20:23], v[158:161], v[216:219], v[20:23]
	v_mfma_f32_16x16x32_bf16 v[16:19], v[166:169], v[216:219], v[16:19]
	v_mfma_f32_16x16x32_bf16 v[44:47], v[170:173], v[186:189], v[44:47]
	v_mfma_f32_16x16x32_bf16 v[40:43], v[178:181], v[186:189], v[40:43]
	v_mfma_f32_16x16x32_bf16 v[28:31], v[170:173], v[196:199], v[28:31]
	v_mfma_f32_16x16x32_bf16 v[24:27], v[178:181], v[196:199], v[24:27]
	v_mfma_f32_16x16x32_bf16 v[12:15], v[170:173], v[204:207], v[12:15]
	v_mfma_f32_16x16x32_bf16 v[8:11], v[178:181], v[204:207], v[8:11]
	v_mfma_f32_16x16x32_bf16 v[4:7], v[170:173], v[212:215], v[4:7]
	v_mfma_f32_16x16x32_bf16 v[0:3], v[178:181], v[212:215], v[0:3]
	v_mfma_f32_16x16x32_bf16 v[44:47], v[174:177], v[192:195], v[44:47]
	v_mfma_f32_16x16x32_bf16 v[40:43], v[182:185], v[192:195], v[40:43]
	v_mfma_f32_16x16x32_bf16 v[28:31], v[174:177], v[200:203], v[28:31]
	v_mfma_f32_16x16x32_bf16 v[24:27], v[182:185], v[200:203], v[24:27]
	v_mfma_f32_16x16x32_bf16 v[12:15], v[174:177], v[208:211], v[12:15]
	v_mfma_f32_16x16x32_bf16 v[8:11], v[182:185], v[208:211], v[8:11]
	v_mfma_f32_16x16x32_bf16 v[4:7], v[174:177], v[216:219], v[4:7]
	v_mfma_f32_16x16x32_bf16 v[0:3], v[182:185], v[216:219], v[0:3]
	s_barrier
	s_add_i32 s91, 0, 0x18000
	v_add_u32_e32 v149, s91, v147
	s_add_i32 s92, 0, 0x1c000
	ds_read_b128 v[154:157], v149
	ds_read_b128 v[158:161], v149 offset:1024
	ds_read_b128 v[162:165], v149 offset:2048
	ds_read_b128 v[166:169], v149 offset:3072
	v_add_u32_e32 v149, s92, v147
	ds_read_b128 v[170:173], v149
	ds_read_b128 v[174:177], v149 offset:1024
	ds_read_b128 v[178:181], v149 offset:2048
	ds_read_b128 v[182:185], v149 offset:3072
	s_add_u32 s62, s62, 0x480000
	s_addc_u32 s63, s63, 0
	s_mov_b32 m0, s71
	v_lshl_add_u64 v[228:229], s[62:63], 0, v[128:129]
	ds_read_b128 v[186:189], v148 offset:32768
	ds_read_b128 v[192:195], v148 offset:33792
	ds_read_b128 v[196:199], v148 offset:34816
	ds_read_b128 v[200:203], v148 offset:35840
	ds_read_b128 v[204:207], v148 offset:36864
	ds_read_b128 v[208:211], v148 offset:37888
	ds_read_b128 v[212:215], v148 offset:38912
	ds_read_b128 v[216:219], v148 offset:39936
	global_load_lds_dwordx4 v[228:229], off
	s_mov_b32 m0, s72
	v_lshl_add_u64 v[228:229], s[62:63], 0, v[130:131]
	global_load_lds_dwordx4 v[228:229], off
	s_waitcnt vmcnt(8)
	s_waitcnt lgkmcnt(0)
	s_barrier
	s_waitcnt lgkmcnt(0)
	v_mfma_f32_16x16x32_bf16 v[124:127], v[154:157], v[186:189], v[124:127]
	v_mfma_f32_16x16x32_bf16 v[120:123], v[162:165], v[186:189], v[120:123]
	v_mfma_f32_16x16x32_bf16 v[116:119], v[154:157], v[196:199], v[116:119]
	v_mfma_f32_16x16x32_bf16 v[112:115], v[162:165], v[196:199], v[112:115]
	v_mfma_f32_16x16x32_bf16 v[100:103], v[154:157], v[204:207], v[100:103]
	v_mfma_f32_16x16x32_bf16 v[96:99], v[162:165], v[204:207], v[96:99]
	v_mfma_f32_16x16x32_bf16 v[84:87], v[154:157], v[212:215], v[84:87]
	v_mfma_f32_16x16x32_bf16 v[80:83], v[162:165], v[212:215], v[80:83]
	v_mfma_f32_16x16x32_bf16 v[124:127], v[158:161], v[192:195], v[124:127]
	v_mfma_f32_16x16x32_bf16 v[120:123], v[166:169], v[192:195], v[120:123]
	v_mfma_f32_16x16x32_bf16 v[116:119], v[158:161], v[200:203], v[116:119]
	v_mfma_f32_16x16x32_bf16 v[112:115], v[166:169], v[200:203], v[112:115]
	v_mfma_f32_16x16x32_bf16 v[100:103], v[158:161], v[208:211], v[100:103]
	v_mfma_f32_16x16x32_bf16 v[96:99], v[166:169], v[208:211], v[96:99]
	v_mfma_f32_16x16x32_bf16 v[84:87], v[158:161], v[216:219], v[84:87]
	v_mfma_f32_16x16x32_bf16 v[80:83], v[166:169], v[216:219], v[80:83]
	v_mfma_f32_16x16x32_bf16 v[108:111], v[170:173], v[186:189], v[108:111]
	v_mfma_f32_16x16x32_bf16 v[104:107], v[178:181], v[186:189], v[104:107]
	v_mfma_f32_16x16x32_bf16 v[92:95], v[170:173], v[196:199], v[92:95]
	v_mfma_f32_16x16x32_bf16 v[88:91], v[178:181], v[196:199], v[88:91]
	v_mfma_f32_16x16x32_bf16 v[76:79], v[170:173], v[204:207], v[76:79]
	v_mfma_f32_16x16x32_bf16 v[72:75], v[178:181], v[204:207], v[72:75]
	v_mfma_f32_16x16x32_bf16 v[68:71], v[170:173], v[212:215], v[68:71]
	v_mfma_f32_16x16x32_bf16 v[64:67], v[178:181], v[212:215], v[64:67]
	v_mfma_f32_16x16x32_bf16 v[108:111], v[174:177], v[192:195], v[108:111]
	v_mfma_f32_16x16x32_bf16 v[104:107], v[182:185], v[192:195], v[104:107]
	v_mfma_f32_16x16x32_bf16 v[92:95], v[174:177], v[200:203], v[92:95]
	v_mfma_f32_16x16x32_bf16 v[88:91], v[182:185], v[200:203], v[88:91]
	v_mfma_f32_16x16x32_bf16 v[76:79], v[174:177], v[208:211], v[76:79]
	v_mfma_f32_16x16x32_bf16 v[72:75], v[182:185], v[208:211], v[72:75]
	v_mfma_f32_16x16x32_bf16 v[68:71], v[174:177], v[216:219], v[68:71]
	v_mfma_f32_16x16x32_bf16 v[64:67], v[182:185], v[216:219], v[64:67]
	s_barrier
; #define PG8_STAGE(bufoff, gbase, voff) do { _Pragma("unroll") for (int _i = 0; _i < 2; ++_i) \
;         __builtin_amdgcn_global_load_lds((const unsigned*)((const char*)(gbase) + (voff)[_i]), (LAS unsigned*)(lds + (bufoff) + ldsw + _i * 8192), 16, 0, 0); } while (0)
; #define PG8_LDA(dst, b, h) do { _Pragma("unroll") for (int m = 0; m < 4; ++m) _Pragma("unroll") for (int k = 0; k < 2; ++k) dst[m][k] = *(const LAS bf16x8*)(lds + PG8_SA(b, h) + aoff + m * 2048 + k * 1024); } while (0)
; #define PG8_MMA(ai, bj, At, Bt) do { __builtin_amdgcn_s_setprio(1); _Pragma("unroll") for (int m = 0; m < 4; ++m) _Pragma("unroll") for (int n = 0; n < 2; ++n) _Pragma("unroll") for (int k = 0; k < 2; ++k) \
;         acc[ai][bj][m][n] = __builtin_amdgcn_mfma_f32_16x16x32_bf16(Bt[n][k], At[m][k], acc[ai][bj][m][n], 0, 0, 0); __builtin_amdgcn_s_setprio(0); } while (0)
; #define PG8_WAIT_V(n) asm volatile("s_waitcnt vmcnt(" #n ")" ::: "memory")
; #define PG8_WAIT_L(n) asm volatile("s_waitcnt lgkmcnt(" #n ")" ::: "memory")
; #define PG8_BAR __builtin_amdgcn_s_barrier()
; #define PG8_SCHED __builtin_amdgcn_sched_barrier(0)
; template <class Epi, bool ALIGN_EPI = true, bool SP2 = true>
; DI void gemm_phase(LAS unsigned char* lds, const Gemm g, const StaticOrder& S, const Epi& E) {
;     ...
;             PG8_LDA(At, 1, 1); PG8_STAGE(PG8_SB(1, 0), b3, voffB); PG8_STAGE(PG8_SB(1, 1), b3 + hstepB, voffB); PG8_STAGE(PG8_SA(1, 0), a3, voffA);
;             PG8_WAIT_V(8); PG8_WAIT_L(0); PG8_BAR; PG8_MMA(1, 0, At, B0); PG8_MMA(1, 1, At, B1); PG8_BAR; PG8_SCHED;
;     ...
;         if constexpr (ALIGN_EPI) { if (wr == 0) PG8_BAR; }
	s_add_i32 s62, s91, s68
	v_lshl_add_u64 v[150:151], v[150:151], 0, s[20:21]
	s_mov_b32 m0, s62
	ds_read_b128 v[186:189], v148 offset:49152
	ds_read_b128 v[192:195], v148 offset:50176
	ds_read_b128 v[196:199], v148 offset:51200
	ds_read_b128 v[200:203], v148 offset:52224
	ds_read_b128 v[204:207], v148 offset:53248
	ds_read_b128 v[208:211], v148 offset:54272
	ds_read_b128 v[212:215], v148 offset:55296
	ds_read_b128 v[216:219], v148 offset:56320
	global_load_lds_dwordx4 v[150:151], off
	s_add_i32 m0, s62, 0x2000
	s_add_u32 s60, s60, 0x20080
	v_lshl_add_u64 v[150:151], v[220:221], 0, s[20:21]
	s_addc_u32 s61, s61, 0
	s_add_i32 s62, s92, s68
	global_load_lds_dwordx4 v[150:151], off
	s_mov_b32 m0, s62
	v_lshl_add_u64 v[150:151], s[60:61], 0, v[132:133]
	global_load_lds_dwordx4 v[150:151], off
	s_add_i32 m0, s62, 0x2000
	v_lshl_add_u64 v[150:151], s[60:61], 0, v[134:135]
	global_load_lds_dwordx4 v[150:151], off
	s_mov_b32 m0, s74
	v_lshl_add_u64 v[150:151], v[222:223], 0, s[20:21]
	global_load_lds_dwordx4 v[150:151], off
	s_mov_b32 m0, s75
	v_lshl_add_u64 v[150:151], v[226:227], 0, s[20:21]
	global_load_lds_dwordx4 v[150:151], off
	s_waitcnt vmcnt(8)
	s_waitcnt lgkmcnt(0)
	s_barrier
	s_waitcnt lgkmcnt(0)
	v_mfma_f32_16x16x32_bf16 v[60:63], v[154:157], v[186:189], v[60:63]
	v_mfma_f32_16x16x32_bf16 v[56:59], v[162:165], v[186:189], v[56:59]
	v_mfma_f32_16x16x32_bf16 v[52:55], v[154:157], v[196:199], v[52:55]
	v_mfma_f32_16x16x32_bf16 v[48:51], v[162:165], v[196:199], v[48:51]
	v_mfma_f32_16x16x32_bf16 v[36:39], v[154:157], v[204:207], v[36:39]
	v_mfma_f32_16x16x32_bf16 v[32:35], v[162:165], v[204:207], v[32:35]
	v_mfma_f32_16x16x32_bf16 v[20:23], v[154:157], v[212:215], v[20:23]
	v_mfma_f32_16x16x32_bf16 v[16:19], v[162:165], v[212:215], v[16:19]
	v_mfma_f32_16x16x32_bf16 v[60:63], v[158:161], v[192:195], v[60:63]
	v_mfma_f32_16x16x32_bf16 v[56:59], v[166:169], v[192:195], v[56:59]
	v_mfma_f32_16x16x32_bf16 v[52:55], v[158:161], v[200:203], v[52:55]
	v_mfma_f32_16x16x32_bf16 v[48:51], v[166:169], v[200:203], v[48:51]
	v_mfma_f32_16x16x32_bf16 v[36:39], v[158:161], v[208:211], v[36:39]
	v_mfma_f32_16x16x32_bf16 v[32:35], v[166:169], v[208:211], v[32:35]
	v_mfma_f32_16x16x32_bf16 v[20:23], v[158:161], v[216:219], v[20:23]
	v_mfma_f32_16x16x32_bf16 v[16:19], v[166:169], v[216:219], v[16:19]
	v_mfma_f32_16x16x32_bf16 v[44:47], v[170:173], v[186:189], v[44:47]
	v_mfma_f32_16x16x32_bf16 v[40:43], v[178:181], v[186:189], v[40:43]
	v_mfma_f32_16x16x32_bf16 v[28:31], v[170:173], v[196:199], v[28:31]
	v_mfma_f32_16x16x32_bf16 v[24:27], v[178:181], v[196:199], v[24:27]
	v_mfma_f32_16x16x32_bf16 v[12:15], v[170:173], v[204:207], v[12:15]
	v_mfma_f32_16x16x32_bf16 v[8:11], v[178:181], v[204:207], v[8:11]
	v_mfma_f32_16x16x32_bf16 v[4:7], v[170:173], v[212:215], v[4:7]
	v_mfma_f32_16x16x32_bf16 v[0:3], v[178:181], v[212:215], v[0:3]
	v_mfma_f32_16x16x32_bf16 v[44:47], v[174:177], v[192:195], v[44:47]
	v_mfma_f32_16x16x32_bf16 v[40:43], v[182:185], v[192:195], v[40:43]
	v_mfma_f32_16x16x32_bf16 v[28:31], v[174:177], v[200:203], v[28:31]
	v_mfma_f32_16x16x32_bf16 v[24:27], v[182:185], v[200:203], v[24:27]
	v_mfma_f32_16x16x32_bf16 v[12:15], v[174:177], v[208:211], v[12:15]
	v_mfma_f32_16x16x32_bf16 v[8:11], v[182:185], v[208:211], v[8:11]
	v_mfma_f32_16x16x32_bf16 v[4:7], v[174:177], v[216:219], v[4:7]
	v_mfma_f32_16x16x32_bf16 v[0:3], v[182:185], v[216:219], v[0:3]
	s_barrier
	s_add_i32 s90, s90, 2
	s_add_u32 s0, s0, 0x100
	s_addc_u32 s1, s1, 0
	s_add_u32 s88, s88, 0x100
	s_addc_u32 s89, s89, 0
	s_cmp_gt_u32 s90, 5
	s_cbranch_scc0 .LBB0_360
	s_and_b64 vcc, exec, s[22:23]
	s_cbranch_vccz .LBB0_363
	s_barrier

; #define PG8_STAGE(bufoff, gbase, voff) do { _Pragma("unroll") for (int _i = 0; _i < 2; ++_i) \
;         __builtin_amdgcn_global_load_lds((const unsigned*)((const char*)(gbase) + (voff)[_i]), (LAS unsigned*)(lds + (bufoff) + ldsw + _i * 8192), 16, 0, 0); } while (0)
; #define PG8_LDA(dst, b, h) do { _Pragma("unroll") for (int m = 0; m < 4; ++m) _Pragma("unroll") for (int k = 0; k < 2; ++k) dst[m][k] = *(const LAS bf16x8*)(lds + PG8_SA(b, h) + aoff + m * 2048 + k * 1024); } while (0)
; #define PG8_LDB(dst, b, h) do { _Pragma("unroll") for (int n = 0; n < 2; ++n) _Pragma("unroll") for (int k = 0; k < 2; ++k) dst[n][k] = *(const LAS bf16x8*)(lds + PG8_SB(b, h) + boff + n * 2048 + k * 1024); } while (0)
; #define PG8_MMA(ai, bj, At, Bt) do { __builtin_amdgcn_s_setprio(1); _Pragma("unroll") for (int m = 0; m < 4; ++m) _Pragma("unroll") for (int n = 0; n < 2; ++n) _Pragma("unroll") for (int k = 0; k < 2; ++k) \
;         acc[ai][bj][m][n] = __builtin_amdgcn_mfma_f32_16x16x32_bf16(Bt[n][k], At[m][k], acc[ai][bj][m][n], 0, 0, 0); __builtin_amdgcn_s_setprio(0); } while (0)
; #define PG8_WAIT_V(n) asm volatile("s_waitcnt vmcnt(" #n ")" ::: "memory")
; #define PG8_WAIT_L(n) asm volatile("s_waitcnt lgkmcnt(" #n ")" ::: "memory")
; template <class Epi, bool ALIGN_EPI = true, bool SP2 = true>
; DI void gemm_phase(LAS unsigned char* lds, const Gemm g, const StaticOrder& S, const Epi& E) {
;     ...
;             const bool last = (t == nt - 2);
;             const char* a1 = cA + (size_t)(t + 1) * kstep;
;             const char* a2 = last ? nA : cA + (size_t)(t + 2) * kstep; const char* b2 = last ? nB : cB + (size_t)(t + 2) * kstep;
;             const char* a3 = a2 + kstep; const char* b3 = b2 + kstep;
;             if (Epi::MID) { if (t == (nt >> 1)) {
;                 if constexpr (ALIGN_EPI) { if (wr == 0) PG8_BAR; }
;                 E.mid(acc, cur, wr, wc, fr, fq);
;                 if constexpr (ALIGN_EPI) { if (wr == 1) PG8_BAR; } } }
;             if constexpr (SP2) {
;             PG8_LDB(B0, 0, 0); PG8_LDB(B1, 0, 1); PG8_SCHED; PG8_LDA(At, 0, 0); PG8_STAGE(PG8_SA(1, 1), a1 + hstepA, voffA);
;             PG8_WAIT_V(8); PG8_WAIT_L(0); PG8_BAR; PG8_MMA(0, 0, At, B0); PG8_MMA(0, 1, At, B1); PG8_BAR; PG8_SCHED;
;             PG8_LDA(At, 0, 1); PG8_STAGE(PG8_SB(0, 0), b2, voffB); PG8_STAGE(PG8_SB(0, 1), b2 + hstepB, voffB); PG8_STAGE(PG8_SA(0, 0), a2, voffA);
.LBB0_755:
	v_add_u32_e32 v1, s67, v227
	ds_read_b128 v[132:135], v1
	ds_read_b128 v[136:139], v1 offset:1024
	ds_read_b128 v[140:143], v1 offset:2048
	ds_read_b128 v[144:147], v1 offset:3072
	v_add_u32_e32 v1, s68, v227
	s_add_u32 s8, s26, s30
	ds_read_b128 v[148:151], v1
	ds_read_b128 v[152:155], v1 offset:1024
	ds_read_b128 v[156:159], v1 offset:2048
	ds_read_b128 v[160:163], v1 offset:3072
	s_addc_u32 s9, s27, s31
	s_add_u32 s8, s8, 0x100
	s_addc_u32 s9, s9, 0
	s_add_u32 s34, s73, s30
	s_addc_u32 s35, s74, s31
	s_cmpk_eq_i32 s30, 0x1f00
	s_cselect_b32 s37, s21, s9
	s_cselect_b32 s36, s69, s8
	s_cselect_b32 s35, s70, s35
	s_cselect_b32 s34, s71, s34
	v_lshl_add_u64 v[2:3], v[188:189], 0, s[30:31]
	s_add_i32 m0, s43, 0xc000
	ds_read_b128 v[164:167], v229
	ds_read_b128 v[168:171], v229 offset:1024
	ds_read_b128 v[172:175], v229 offset:2048
	ds_read_b128 v[176:179], v229 offset:3072
	ds_read_b128 v[180:183], v229 offset:4096
	ds_read_b128 v[184:187], v229 offset:5120
	ds_read_b128 v[212:215], v229 offset:6144
	ds_read_b128 v[216:219], v229 offset:7168
	global_load_lds_dwordx4 v[2:3], off
	s_add_i32 m0, s43, 0xe000
	v_lshl_add_u64 v[2:3], v[190:191], 0, s[30:31]
	global_load_lds_dwordx4 v[2:3], off
	s_waitcnt vmcnt(8)
	s_waitcnt lgkmcnt(0)
	s_barrier
	s_waitcnt lgkmcnt(0)
	v_mfma_f32_16x16x32_bf16 v[128:131], v[132:135], v[164:167], v[128:131]
	v_mfma_f32_16x16x32_bf16 v[124:127], v[140:143], v[164:167], v[124:127]
	v_mfma_f32_16x16x32_bf16 v[112:115], v[132:135], v[172:175], v[112:115]
	v_mfma_f32_16x16x32_bf16 v[108:111], v[140:143], v[172:175], v[108:111]
	v_mfma_f32_16x16x32_bf16 v[96:99], v[132:135], v[180:183], v[96:99]
	v_mfma_f32_16x16x32_bf16 v[92:95], v[140:143], v[180:183], v[92:95]
	v_mfma_f32_16x16x32_bf16 v[80:83], v[132:135], v[212:215], v[80:83]
	v_mfma_f32_16x16x32_bf16 v[76:79], v[140:143], v[212:215], v[76:79]
	v_mfma_f32_16x16x32_bf16 v[128:131], v[136:139], v[168:171], v[128:131]
	v_mfma_f32_16x16x32_bf16 v[124:127], v[144:147], v[168:171], v[124:127]
	v_mfma_f32_16x16x32_bf16 v[112:115], v[136:139], v[176:179], v[112:115]
	v_mfma_f32_16x16x32_bf16 v[108:111], v[144:147], v[176:179], v[108:111]
	v_mfma_f32_16x16x32_bf16 v[96:99], v[136:139], v[184:187], v[96:99]
	v_mfma_f32_16x16x32_bf16 v[92:95], v[144:147], v[184:187], v[92:95]
	v_mfma_f32_16x16x32_bf16 v[80:83], v[136:139], v[216:219], v[80:83]
	v_mfma_f32_16x16x32_bf16 v[76:79], v[144:147], v[216:219], v[76:79]
	v_mfma_f32_16x16x32_bf16 v[120:123], v[148:151], v[164:167], v[120:123]
	v_mfma_f32_16x16x32_bf16 v[116:119], v[156:159], v[164:167], v[116:119]
	v_mfma_f32_16x16x32_bf16 v[104:107], v[148:151], v[172:175], v[104:107]
	v_mfma_f32_16x16x32_bf16 v[100:103], v[156:159], v[172:175], v[100:103]
	v_mfma_f32_16x16x32_bf16 v[88:91], v[148:151], v[180:183], v[88:91]
	v_mfma_f32_16x16x32_bf16 v[84:87], v[156:159], v[180:183], v[84:87]
	v_mfma_f32_16x16x32_bf16 v[72:75], v[148:151], v[212:215], v[72:75]
	v_mfma_f32_16x16x32_bf16 v[68:71], v[156:159], v[212:215], v[68:71]
	v_mfma_f32_16x16x32_bf16 v[120:123], v[152:155], v[168:171], v[120:123]
	v_mfma_f32_16x16x32_bf16 v[116:119], v[160:163], v[168:171], v[116:119]
	v_mfma_f32_16x16x32_bf16 v[104:107], v[152:155], v[176:179], v[104:107]
	v_mfma_f32_16x16x32_bf16 v[100:103], v[160:163], v[176:179], v[100:103]
	v_mfma_f32_16x16x32_bf16 v[88:91], v[152:155], v[184:187], v[88:91]
	v_mfma_f32_16x16x32_bf16 v[84:87], v[160:163], v[184:187], v[84:87]
	v_mfma_f32_16x16x32_bf16 v[72:75], v[152:155], v[216:219], v[72:75]
	v_mfma_f32_16x16x32_bf16 v[68:71], v[160:163], v[216:219], v[68:71]
	s_barrier
	s_add_i32 s8, s67, s42
	v_lshl_add_u64 v[220:221], s[34:35], 0, v[194:195]
	s_mov_b32 m0, s8
	ds_read_b128 v[164:167], v229 offset:16384
	ds_read_b128 v[168:171], v229 offset:17408
	ds_read_b128 v[172:175], v229 offset:18432
	ds_read_b128 v[176:179], v229 offset:19456
	ds_read_b128 v[180:183], v229 offset:20480
	ds_read_b128 v[184:187], v229 offset:21504
	ds_read_b128 v[212:215], v229 offset:22528
	ds_read_b128 v[216:219], v229 offset:23552
	global_load_lds_dwordx4 v[220:221], off
	s_add_i32 m0, s8, 0x2000
	s_add_u32 s76, s34, 0x100000
	v_lshl_add_u64 v[222:223], s[34:35], 0, v[198:199]
	s_addc_u32 s77, s35, 0
	s_add_i32 s8, s68, s42
	global_load_lds_dwordx4 v[222:223], off
	v_lshl_add_u64 v[2:3], s[76:77], 0, v[194:195]
	s_mov_b32 m0, s8
	v_lshl_add_u64 v[232:233], s[36:37], 0, v[192:193]
	global_load_lds_dwordx4 v[2:3], off
	v_lshl_add_u64 v[2:3], s[76:77], 0, v[198:199]
	s_add_i32 m0, s8, 0x2000
	v_lshl_add_u64 v[234:235], s[36:37], 0, v[196:197]
	global_load_lds_dwordx4 v[2:3], off
	s_mov_b32 m0, s43
	s_nop 0
	global_load_lds_dwordx4 v[232:233], off
	s_mov_b32 m0, s44
	s_nop 0
	global_load_lds_dwordx4 v[234:235], off
	s_waitcnt vmcnt(8)
	s_waitcnt lgkmcnt(0)
	s_barrier
; #define PG8_STAGE(bufoff, gbase, voff) do { _Pragma("unroll") for (int _i = 0; _i < 2; ++_i) \
;         __builtin_amdgcn_global_load_lds((const unsigned*)((const char*)(gbase) + (voff)[_i]), (LAS unsigned*)(lds + (bufoff) + ldsw + _i * 8192), 16, 0, 0); } while (0)
; #define PG8_LDA(dst, b, h) do { _Pragma("unroll") for (int m = 0; m < 4; ++m) _Pragma("unroll") for (int k = 0; k < 2; ++k) dst[m][k] = *(const LAS bf16x8*)(lds + PG8_SA(b, h) + aoff + m * 2048 + k * 1024); } while (0)
; #define PG8_LDB(dst, b, h) do { _Pragma("unroll") for (int n = 0; n < 2; ++n) _Pragma("unroll") for (int k = 0; k < 2; ++k) dst[n][k] = *(const LAS bf16x8*)(lds + PG8_SB(b, h) + boff + n * 2048 + k * 1024); } while (0)
; #define PG8_MMA(ai, bj, At, Bt) do { __builtin_amdgcn_s_setprio(1); _Pragma("unroll") for (int m = 0; m < 4; ++m) _Pragma("unroll") for (int n = 0; n < 2; ++n) _Pragma("unroll") for (int k = 0; k < 2; ++k) \
;         acc[ai][bj][m][n] = __builtin_amdgcn_mfma_f32_16x16x32_bf16(Bt[n][k], At[m][k], acc[ai][bj][m][n], 0, 0, 0); __builtin_amdgcn_s_setprio(0); } while (0)
; #define PG8_WAIT_V(n) asm volatile("s_waitcnt vmcnt(" #n ")" ::: "memory")
; #define PG8_WAIT_L(n) asm volatile("s_waitcnt lgkmcnt(" #n ")" ::: "memory")
; #define PG8_BAR __builtin_amdgcn_s_barrier()
; #define PG8_SCHED __builtin_amdgcn_sched_barrier(0)
; template <class Epi, bool ALIGN_EPI = true, bool SP2 = true>
; DI void gemm_phase(LAS unsigned char* lds, const Gemm g, const StaticOrder& S, const Epi& E) {
;     ...
;             PG8_WAIT_V(8); PG8_WAIT_L(0); PG8_BAR; PG8_MMA(1, 0, At, B0); PG8_MMA(1, 1, At, B1); PG8_BAR; PG8_SCHED;
;             PG8_LDB(B0, 1, 0); PG8_LDB(B1, 1, 1); PG8_SCHED; PG8_LDA(At, 1, 0); PG8_STAGE(PG8_SA(0, 1), a2 + hstepA, voffA);
;             PG8_WAIT_V(8); PG8_WAIT_L(0); PG8_BAR; PG8_MMA(0, 0, At, B0); PG8_MMA(0, 1, At, B1); PG8_BAR; PG8_SCHED;
	s_waitcnt lgkmcnt(0)
	v_mfma_f32_16x16x32_bf16 v[64:67], v[132:135], v[164:167], v[64:67]
	v_mfma_f32_16x16x32_bf16 v[60:63], v[140:143], v[164:167], v[60:63]
	v_mfma_f32_16x16x32_bf16 v[48:51], v[132:135], v[172:175], v[48:51]
	v_mfma_f32_16x16x32_bf16 v[44:47], v[140:143], v[172:175], v[44:47]
	v_mfma_f32_16x16x32_bf16 v[32:35], v[132:135], v[180:183], v[32:35]
	v_mfma_f32_16x16x32_bf16 v[28:31], v[140:143], v[180:183], v[28:31]
	v_mfma_f32_16x16x32_bf16 v[16:19], v[132:135], v[212:215], v[16:19]
	v_mfma_f32_16x16x32_bf16 v[12:15], v[140:143], v[212:215], v[12:15]
	v_mfma_f32_16x16x32_bf16 v[64:67], v[136:139], v[168:171], v[64:67]
	v_mfma_f32_16x16x32_bf16 v[60:63], v[144:147], v[168:171], v[60:63]
	v_mfma_f32_16x16x32_bf16 v[48:51], v[136:139], v[176:179], v[48:51]
	v_mfma_f32_16x16x32_bf16 v[44:47], v[144:147], v[176:179], v[44:47]
	v_mfma_f32_16x16x32_bf16 v[32:35], v[136:139], v[184:187], v[32:35]
	v_mfma_f32_16x16x32_bf16 v[28:31], v[144:147], v[184:187], v[28:31]
	v_mfma_f32_16x16x32_bf16 v[16:19], v[136:139], v[216:219], v[16:19]
	v_mfma_f32_16x16x32_bf16 v[12:15], v[144:147], v[216:219], v[12:15]
	v_mfma_f32_16x16x32_bf16 v[56:59], v[148:151], v[164:167], v[56:59]
	v_mfma_f32_16x16x32_bf16 v[52:55], v[156:159], v[164:167], v[52:55]
	v_mfma_f32_16x16x32_bf16 v[40:43], v[148:151], v[172:175], v[40:43]
	v_mfma_f32_16x16x32_bf16 v[36:39], v[156:159], v[172:175], v[36:39]
	v_mfma_f32_16x16x32_bf16 v[24:27], v[148:151], v[180:183], v[24:27]
	v_mfma_f32_16x16x32_bf16 v[20:23], v[156:159], v[180:183], v[20:23]
	v_mfma_f32_16x16x32_bf16 v[8:11], v[148:151], v[212:215], v[8:11]
	v_mfma_f32_16x16x32_bf16 v[2:5], v[156:159], v[212:215], v[4:7]
	v_mfma_f32_16x16x32_bf16 v[56:59], v[152:155], v[168:171], v[56:59]
	v_mfma_f32_16x16x32_bf16 v[52:55], v[160:163], v[168:171], v[52:55]
	v_mfma_f32_16x16x32_bf16 v[40:43], v[152:155], v[176:179], v[40:43]
	v_mfma_f32_16x16x32_bf16 v[36:39], v[160:163], v[176:179], v[36:39]
	v_mfma_f32_16x16x32_bf16 v[24:27], v[152:155], v[184:187], v[24:27]
	v_mfma_f32_16x16x32_bf16 v[20:23], v[160:163], v[184:187], v[20:23]
	v_mfma_f32_16x16x32_bf16 v[8:11], v[152:155], v[216:219], v[8:11]
	v_mfma_f32_16x16x32_bf16 v[2:5], v[160:163], v[216:219], v[2:5]
	s_barrier
	s_add_i32 s8, 0, 0x18000
	v_add_u32_e32 v1, s8, v227
	s_add_i32 s9, 0, 0x1c000
	ds_read_b128 v[132:135], v1
	ds_read_b128 v[136:139], v1 offset:1024
	ds_read_b128 v[140:143], v1 offset:2048
	ds_read_b128 v[144:147], v1 offset:3072
	v_add_u32_e32 v1, s9, v227
	ds_read_b128 v[148:151], v1
	ds_read_b128 v[152:155], v1 offset:1024
	ds_read_b128 v[156:159], v1 offset:2048
	ds_read_b128 v[160:163], v1 offset:3072
	s_add_u32 s36, s36, 0x100000
	s_addc_u32 s37, s37, 0
	s_mov_b32 m0, s45
	v_lshl_add_u64 v[6:7], s[36:37], 0, v[192:193]
	ds_read_b128 v[164:167], v229 offset:32768
	ds_read_b128 v[168:171], v229 offset:33792
	ds_read_b128 v[172:175], v229 offset:34816
	ds_read_b128 v[176:179], v229 offset:35840
	ds_read_b128 v[180:183], v229 offset:36864
	ds_read_b128 v[184:187], v229 offset:37888
	ds_read_b128 v[212:215], v229 offset:38912
	ds_read_b128 v[216:219], v229 offset:39936
	global_load_lds_dwordx4 v[6:7], off
	s_mov_b32 m0, s46
	v_lshl_add_u64 v[6:7], s[36:37], 0, v[196:197]
	global_load_lds_dwordx4 v[6:7], off
	s_waitcnt vmcnt(8)
	s_waitcnt lgkmcnt(0)
	s_barrier
	s_waitcnt lgkmcnt(0)
	v_mfma_f32_16x16x32_bf16 v[128:131], v[132:135], v[164:167], v[128:131]
	v_mfma_f32_16x16x32_bf16 v[124:127], v[140:143], v[164:167], v[124:127]
	v_mfma_f32_16x16x32_bf16 v[112:115], v[132:135], v[172:175], v[112:115]
	v_mfma_f32_16x16x32_bf16 v[108:111], v[140:143], v[172:175], v[108:111]
	v_mfma_f32_16x16x32_bf16 v[96:99], v[132:135], v[180:183], v[96:99]
	v_mfma_f32_16x16x32_bf16 v[92:95], v[140:143], v[180:183], v[92:95]
	v_mfma_f32_16x16x32_bf16 v[80:83], v[132:135], v[212:215], v[80:83]
	v_mfma_f32_16x16x32_bf16 v[76:79], v[140:143], v[212:215], v[76:79]
	v_mfma_f32_16x16x32_bf16 v[128:131], v[136:139], v[168:171], v[128:131]
	v_mfma_f32_16x16x32_bf16 v[124:127], v[144:147], v[168:171], v[124:127]
	v_mfma_f32_16x16x32_bf16 v[112:115], v[136:139], v[176:179], v[112:115]
	v_mfma_f32_16x16x32_bf16 v[108:111], v[144:147], v[176:179], v[108:111]
	v_mfma_f32_16x16x32_bf16 v[96:99], v[136:139], v[184:187], v[96:99]
	v_mfma_f32_16x16x32_bf16 v[92:95], v[144:147], v[184:187], v[92:95]
	v_mfma_f32_16x16x32_bf16 v[80:83], v[136:139], v[216:219], v[80:83]
	v_mfma_f32_16x16x32_bf16 v[76:79], v[144:147], v[216:219], v[76:79]
	v_mfma_f32_16x16x32_bf16 v[120:123], v[148:151], v[164:167], v[120:123]
	v_mfma_f32_16x16x32_bf16 v[116:119], v[156:159], v[164:167], v[116:119]
	v_mfma_f32_16x16x32_bf16 v[104:107], v[148:151], v[172:175], v[104:107]
	v_mfma_f32_16x16x32_bf16 v[100:103], v[156:159], v[172:175], v[100:103]
	v_mfma_f32_16x16x32_bf16 v[88:91], v[148:151], v[180:183], v[88:91]
	v_mfma_f32_16x16x32_bf16 v[84:87], v[156:159], v[180:183], v[84:87]
	v_mfma_f32_16x16x32_bf16 v[72:75], v[148:151], v[212:215], v[72:75]
	v_mfma_f32_16x16x32_bf16 v[68:71], v[156:159], v[212:215], v[68:71]
	v_mfma_f32_16x16x32_bf16 v[120:123], v[152:155], v[168:171], v[120:123]
	v_mfma_f32_16x16x32_bf16 v[116:119], v[160:163], v[168:171], v[116:119]
	v_mfma_f32_16x16x32_bf16 v[104:107], v[152:155], v[176:179], v[104:107]
	v_mfma_f32_16x16x32_bf16 v[100:103], v[160:163], v[176:179], v[100:103]
	v_mfma_f32_16x16x32_bf16 v[88:91], v[152:155], v[184:187], v[88:91]
	v_mfma_f32_16x16x32_bf16 v[84:87], v[160:163], v[184:187], v[84:87]
	v_mfma_f32_16x16x32_bf16 v[72:75], v[152:155], v[216:219], v[72:75]
	v_mfma_f32_16x16x32_bf16 v[68:71], v[160:163], v[216:219], v[68:71]
	s_barrier
; #define PG8_STAGE(bufoff, gbase, voff) do { _Pragma("unroll") for (int _i = 0; _i < 2; ++_i) \
;         __builtin_amdgcn_global_load_lds((const unsigned*)((const char*)(gbase) + (voff)[_i]), (LAS unsigned*)(lds + (bufoff) + ldsw + _i * 8192), 16, 0, 0); } while (0)
; #define PG8_LDA(dst, b, h) do { _Pragma("unroll") for (int m = 0; m < 4; ++m) _Pragma("unroll") for (int k = 0; k < 2; ++k) dst[m][k] = *(const LAS bf16x8*)(lds + PG8_SA(b, h) + aoff + m * 2048 + k * 1024); } while (0)
; #define PG8_MMA(ai, bj, At, Bt) do { __builtin_amdgcn_s_setprio(1); _Pragma("unroll") for (int m = 0; m < 4; ++m) _Pragma("unroll") for (int n = 0; n < 2; ++n) _Pragma("unroll") for (int k = 0; k < 2; ++k) \
;         acc[ai][bj][m][n] = __builtin_amdgcn_mfma_f32_16x16x32_bf16(Bt[n][k], At[m][k], acc[ai][bj][m][n], 0, 0, 0); __builtin_amdgcn_s_setprio(0); } while (0)
; #define PG8_WAIT_V(n) asm volatile("s_waitcnt vmcnt(" #n ")" ::: "memory")
; #define PG8_WAIT_L(n) asm volatile("s_waitcnt lgkmcnt(" #n ")" ::: "memory")
; #define PG8_BAR __builtin_amdgcn_s_barrier()
; #define PG8_SCHED __builtin_amdgcn_sched_barrier(0)
; template <class Epi, bool ALIGN_EPI = true, bool SP2 = true>
; DI void gemm_phase(LAS unsigned char* lds, const Gemm g, const StaticOrder& S, const Epi& E) {
;     ...
;             PG8_LDA(At, 1, 1); PG8_STAGE(PG8_SB(1, 0), b3, voffB); PG8_STAGE(PG8_SB(1, 1), b3 + hstepB, voffB); PG8_STAGE(PG8_SA(1, 0), a3, voffA);
;             PG8_WAIT_V(8); PG8_WAIT_L(0); PG8_BAR; PG8_MMA(1, 0, At, B0); PG8_MMA(1, 1, At, B1); PG8_BAR; PG8_SCHED;
	s_add_i32 s8, s8, s42
	v_lshl_add_u64 v[6:7], v[220:221], 0, s[10:11]
	s_mov_b32 m0, s8
	ds_read_b128 v[164:167], v229 offset:49152
	ds_read_b128 v[168:171], v229 offset:50176
	ds_read_b128 v[172:175], v229 offset:51200
	ds_read_b128 v[176:179], v229 offset:52224
	ds_read_b128 v[180:183], v229 offset:53248
	ds_read_b128 v[184:187], v229 offset:54272
	ds_read_b128 v[212:215], v229 offset:55296
	ds_read_b128 v[216:219], v229 offset:56320
	global_load_lds_dwordx4 v[6:7], off
	s_add_i32 m0, s8, 0x2000
	s_add_u32 s34, s34, 0x100080
	v_lshl_add_u64 v[6:7], v[222:223], 0, s[10:11]
	s_addc_u32 s35, s35, 0
	s_add_i32 s8, s9, s42
	global_load_lds_dwordx4 v[6:7], off
	s_mov_b32 m0, s8
	v_lshl_add_u64 v[6:7], s[34:35], 0, v[194:195]
	global_load_lds_dwordx4 v[6:7], off
	s_add_i32 m0, s8, 0x2000
	v_lshl_add_u64 v[6:7], s[34:35], 0, v[198:199]
	global_load_lds_dwordx4 v[6:7], off
	s_mov_b32 m0, s51
	v_lshl_add_u64 v[6:7], v[232:233], 0, s[10:11]
	global_load_lds_dwordx4 v[6:7], off
	s_mov_b32 m0, s60
	v_lshl_add_u64 v[6:7], v[234:235], 0, s[10:11]
	global_load_lds_dwordx4 v[6:7], off
	s_waitcnt vmcnt(8)
	s_waitcnt lgkmcnt(0)
	s_barrier
	s_waitcnt lgkmcnt(0)
	v_mfma_f32_16x16x32_bf16 v[64:67], v[132:135], v[164:167], v[64:67]
	v_mfma_f32_16x16x32_bf16 v[60:63], v[140:143], v[164:167], v[60:63]
	v_mfma_f32_16x16x32_bf16 v[48:51], v[132:135], v[172:175], v[48:51]
	v_mfma_f32_16x16x32_bf16 v[44:47], v[140:143], v[172:175], v[44:47]
	v_mfma_f32_16x16x32_bf16 v[32:35], v[132:135], v[180:183], v[32:35]
	v_mfma_f32_16x16x32_bf16 v[28:31], v[140:143], v[180:183], v[28:31]
	v_mfma_f32_16x16x32_bf16 v[16:19], v[132:135], v[212:215], v[16:19]
	v_mfma_f32_16x16x32_bf16 v[12:15], v[140:143], v[212:215], v[12:15]
	v_mfma_f32_16x16x32_bf16 v[64:67], v[136:139], v[168:171], v[64:67]
	v_mfma_f32_16x16x32_bf16 v[60:63], v[144:147], v[168:171], v[60:63]
	v_mfma_f32_16x16x32_bf16 v[48:51], v[136:139], v[176:179], v[48:51]
	v_mfma_f32_16x16x32_bf16 v[44:47], v[144:147], v[176:179], v[44:47]
	v_mfma_f32_16x16x32_bf16 v[32:35], v[136:139], v[184:187], v[32:35]
	v_mfma_f32_16x16x32_bf16 v[28:31], v[144:147], v[184:187], v[28:31]
	v_mfma_f32_16x16x32_bf16 v[16:19], v[136:139], v[216:219], v[16:19]
	v_mfma_f32_16x16x32_bf16 v[12:15], v[144:147], v[216:219], v[12:15]
	v_mfma_f32_16x16x32_bf16 v[56:59], v[148:151], v[164:167], v[56:59]
	v_mfma_f32_16x16x32_bf16 v[52:55], v[156:159], v[164:167], v[52:55]
	v_mfma_f32_16x16x32_bf16 v[40:43], v[148:151], v[172:175], v[40:43]
	v_mfma_f32_16x16x32_bf16 v[36:39], v[156:159], v[172:175], v[36:39]
	v_mfma_f32_16x16x32_bf16 v[24:27], v[148:151], v[180:183], v[24:27]
	v_mfma_f32_16x16x32_bf16 v[20:23], v[156:159], v[180:183], v[20:23]
	v_mfma_f32_16x16x32_bf16 v[6:9], v[148:151], v[212:215], v[8:11]
	v_mfma_f32_16x16x32_bf16 v[2:5], v[156:159], v[212:215], v[2:5]
	v_mfma_f32_16x16x32_bf16 v[56:59], v[152:155], v[168:171], v[56:59]
	v_mfma_f32_16x16x32_bf16 v[52:55], v[160:163], v[168:171], v[52:55]
	v_mfma_f32_16x16x32_bf16 v[40:43], v[152:155], v[176:179], v[40:43]
	v_mfma_f32_16x16x32_bf16 v[36:39], v[160:163], v[176:179], v[36:39]
	v_mfma_f32_16x16x32_bf16 v[24:27], v[152:155], v[184:187], v[24:27]
	v_mfma_f32_16x16x32_bf16 v[20:23], v[160:163], v[184:187], v[20:23]
	v_mfma_f32_16x16x32_bf16 v[8:11], v[152:155], v[216:219], v[6:9]
	v_mfma_f32_16x16x32_bf16 v[4:7], v[160:163], v[216:219], v[2:5]
	s_barrier
	s_add_i32 s75, s75, 2
	s_add_u32 s30, s30, 0x100
	s_addc_u32 s31, s31, 0
	s_cmp_gt_u32 s75, 61
	s_cbranch_scc1 .LBB0_761

; #define PG8_STAGE(bufoff, gbase, voff) do { _Pragma("unroll") for (int _i = 0; _i < 2; ++_i) \
;         __builtin_amdgcn_global_load_lds((const unsigned*)((const char*)(gbase) + (voff)[_i]), (LAS unsigned*)(lds + (bufoff) + ldsw + _i * 8192), 16, 0, 0); } while (0)
; #define PG8_LDA(dst, b, h) do { _Pragma("unroll") for (int m = 0; m < 4; ++m) _Pragma("unroll") for (int k = 0; k < 2; ++k) dst[m][k] = *(const LAS bf16x8*)(lds + PG8_SA(b, h) + aoff + m * 2048 + k * 1024); } while (0)
; #define PG8_LDB(dst, b, h) do { _Pragma("unroll") for (int n = 0; n < 2; ++n) _Pragma("unroll") for (int k = 0; k < 2; ++k) dst[n][k] = *(const LAS bf16x8*)(lds + PG8_SB(b, h) + boff + n * 2048 + k * 1024); } while (0)
; #define PG8_MMA(ai, bj, At, Bt) do { __builtin_amdgcn_s_setprio(1); _Pragma("unroll") for (int m = 0; m < 4; ++m) _Pragma("unroll") for (int n = 0; n < 2; ++n) _Pragma("unroll") for (int k = 0; k < 2; ++k) \
;         acc[ai][bj][m][n] = __builtin_amdgcn_mfma_f32_16x16x32_bf16(Bt[n][k], At[m][k], acc[ai][bj][m][n], 0, 0, 0); __builtin_amdgcn_s_setprio(0); } while (0)
; #define PG8_WAIT_V(n) asm volatile("s_waitcnt vmcnt(" #n ")" ::: "memory")
; #define PG8_WAIT_L(n) asm volatile("s_waitcnt lgkmcnt(" #n ")" ::: "memory")
; template <class Epi, bool ALIGN_EPI = true, bool SP2 = true>
; DI void gemm_phase(LAS unsigned char* lds, const Gemm g, const StaticOrder& S, const Epi& E) {
;     ...
;             const bool last = (t == nt - 2);
;             const char* a1 = cA + (size_t)(t + 1) * kstep;
;             const char* a2 = last ? nA : cA + (size_t)(t + 2) * kstep; const char* b2 = last ? nB : cB + (size_t)(t + 2) * kstep;
;             const char* a3 = a2 + kstep; const char* b3 = b2 + kstep;
;             if (Epi::MID) { if (t == (nt >> 1)) {
;                 if constexpr (ALIGN_EPI) { if (wr == 0) PG8_BAR; }
;                 E.mid(acc, cur, wr, wc, fr, fq);
;                 if constexpr (ALIGN_EPI) { if (wr == 1) PG8_BAR; } } }
;             if constexpr (SP2) {
;             PG8_LDB(B0, 0, 0); PG8_LDB(B1, 0, 1); PG8_SCHED; PG8_LDA(At, 0, 0); PG8_STAGE(PG8_SA(1, 1), a1 + hstepA, voffA);
;             PG8_WAIT_V(8); PG8_WAIT_L(0); PG8_BAR; PG8_MMA(0, 0, At, B0); PG8_MMA(0, 1, At, B1); PG8_BAR; PG8_SCHED;
;             PG8_LDA(At, 0, 1); PG8_STAGE(PG8_SB(0, 0), b2, voffB); PG8_STAGE(PG8_SB(0, 1), b2 + hstepB, voffB); PG8_STAGE(PG8_SA(0, 0), a2, voffA);
.LBB0_839:
	ds_read_b128 v[140:143], v149
	ds_read_b128 v[152:155], v149 offset:1024
	ds_read_b128 v[156:159], v149 offset:2048
	ds_read_b128 v[160:163], v149 offset:3072
	ds_read_b128 v[164:167], v150
	ds_read_b128 v[168:171], v150 offset:1024
	ds_read_b128 v[172:175], v150 offset:2048
	ds_read_b128 v[176:179], v150 offset:3072
	s_add_u32 s34, s30, 0xfff00080
	s_addc_u32 s35, s31, -1
	s_cmp_eq_u32 s59, 60
	s_cselect_b32 s37, s23, s35
	s_cselect_b32 s36, s50, s34
	s_cselect_b32 s35, s21, s57
	s_cselect_b32 s34, s51, s56
	v_lshl_add_u64 v[144:145], s[30:31], 0, v[132:133]
	s_add_i32 m0, s29, 0xc000
	ds_read_b128 v[180:183], v151
	ds_read_b128 v[184:187], v151 offset:1024
	ds_read_b128 v[188:191], v151 offset:2048
	ds_read_b128 v[192:195], v151 offset:3072
	ds_read_b128 v[196:199], v151 offset:4096
	ds_read_b128 v[200:203], v151 offset:5120
	ds_read_b128 v[204:207], v151 offset:6144
	ds_read_b128 v[208:211], v151 offset:7168
	global_load_lds_dwordx4 v[144:145], off
	s_add_i32 m0, s29, 0xe000
	v_lshl_add_u64 v[144:145], s[30:31], 0, v[134:135]
	global_load_lds_dwordx4 v[144:145], off
	s_waitcnt vmcnt(8)
	s_waitcnt lgkmcnt(0)
	s_barrier
	s_waitcnt lgkmcnt(0)
	v_mfma_f32_16x16x32_bf16 v[124:127], v[140:143], v[180:183], v[124:127]
	v_mfma_f32_16x16x32_bf16 v[120:123], v[156:159], v[180:183], v[120:123]
	v_mfma_f32_16x16x32_bf16 v[116:119], v[140:143], v[188:191], v[116:119]
	v_mfma_f32_16x16x32_bf16 v[112:115], v[156:159], v[188:191], v[112:115]
	v_mfma_f32_16x16x32_bf16 v[108:111], v[140:143], v[196:199], v[108:111]
	v_mfma_f32_16x16x32_bf16 v[100:103], v[156:159], v[196:199], v[100:103]
	v_mfma_f32_16x16x32_bf16 v[92:95], v[140:143], v[204:207], v[92:95]
	v_mfma_f32_16x16x32_bf16 v[80:83], v[156:159], v[204:207], v[80:83]
	v_mfma_f32_16x16x32_bf16 v[124:127], v[152:155], v[184:187], v[124:127]
	v_mfma_f32_16x16x32_bf16 v[120:123], v[160:163], v[184:187], v[120:123]
	v_mfma_f32_16x16x32_bf16 v[116:119], v[152:155], v[192:195], v[116:119]
	v_mfma_f32_16x16x32_bf16 v[112:115], v[160:163], v[192:195], v[112:115]
	v_mfma_f32_16x16x32_bf16 v[108:111], v[152:155], v[200:203], v[108:111]
	v_mfma_f32_16x16x32_bf16 v[100:103], v[160:163], v[200:203], v[100:103]
	v_mfma_f32_16x16x32_bf16 v[92:95], v[152:155], v[208:211], v[92:95]
	v_mfma_f32_16x16x32_bf16 v[80:83], v[160:163], v[208:211], v[80:83]
	v_mfma_f32_16x16x32_bf16 v[104:107], v[164:167], v[180:183], v[104:107]
	v_mfma_f32_16x16x32_bf16 v[96:99], v[172:175], v[180:183], v[96:99]
	v_mfma_f32_16x16x32_bf16 v[88:91], v[164:167], v[188:191], v[88:91]
	v_mfma_f32_16x16x32_bf16 v[84:87], v[172:175], v[188:191], v[84:87]
	v_mfma_f32_16x16x32_bf16 v[76:79], v[164:167], v[196:199], v[76:79]
	v_mfma_f32_16x16x32_bf16 v[72:75], v[172:175], v[196:199], v[72:75]
	v_mfma_f32_16x16x32_bf16 v[68:71], v[164:167], v[204:207], v[68:71]
	v_mfma_f32_16x16x32_bf16 v[64:67], v[172:175], v[204:207], v[64:67]
	v_mfma_f32_16x16x32_bf16 v[104:107], v[168:171], v[184:187], v[104:107]
	v_mfma_f32_16x16x32_bf16 v[96:99], v[176:179], v[184:187], v[96:99]
	v_mfma_f32_16x16x32_bf16 v[88:91], v[168:171], v[192:195], v[88:91]
	v_mfma_f32_16x16x32_bf16 v[84:87], v[176:179], v[192:195], v[84:87]
	v_mfma_f32_16x16x32_bf16 v[76:79], v[168:171], v[200:203], v[76:79]
	v_mfma_f32_16x16x32_bf16 v[72:75], v[176:179], v[200:203], v[72:75]
	v_mfma_f32_16x16x32_bf16 v[68:71], v[168:171], v[208:211], v[68:71]
	v_mfma_f32_16x16x32_bf16 v[64:67], v[176:179], v[208:211], v[64:67]
	s_barrier
	s_add_i32 s60, s47, s39
	v_lshl_add_u64 v[144:145], s[34:35], 0, v[128:129]
	s_mov_b32 m0, s60
	ds_read_b128 v[180:183], v151 offset:16384
	ds_read_b128 v[184:187], v151 offset:17408
	ds_read_b128 v[188:191], v151 offset:18432
	ds_read_b128 v[192:195], v151 offset:19456
	ds_read_b128 v[196:199], v151 offset:20480
	ds_read_b128 v[200:203], v151 offset:21504
	ds_read_b128 v[204:207], v151 offset:22528
	ds_read_b128 v[208:211], v151 offset:23552
	global_load_lds_dwordx4 v[144:145], off
	s_add_i32 m0, s60, 0x2000
	s_add_u32 s60, s34, 0x100000
	v_lshl_add_u64 v[212:213], s[34:35], 0, v[130:131]
	s_addc_u32 s61, s35, 0
	s_add_i32 s62, s48, s39
	global_load_lds_dwordx4 v[212:213], off
	v_lshl_add_u64 v[214:215], s[60:61], 0, v[128:129]
	s_mov_b32 m0, s62
	v_lshl_add_u64 v[216:217], s[36:37], 0, v[130:131]
	global_load_lds_dwordx4 v[214:215], off
	s_add_i32 m0, s62, 0x2000
	v_lshl_add_u64 v[214:215], s[60:61], 0, v[130:131]
	global_load_lds_dwordx4 v[214:215], off
	s_mov_b32 m0, s29
	v_lshl_add_u64 v[214:215], s[36:37], 0, v[128:129]
	global_load_lds_dwordx4 v[214:215], off
	s_mov_b32 m0, s40
	s_nop 0
	global_load_lds_dwordx4 v[216:217], off
	s_waitcnt vmcnt(8)
	s_waitcnt lgkmcnt(0)
	s_barrier
; #define PG8_STAGE(bufoff, gbase, voff) do { _Pragma("unroll") for (int _i = 0; _i < 2; ++_i) \
;         __builtin_amdgcn_global_load_lds((const unsigned*)((const char*)(gbase) + (voff)[_i]), (LAS unsigned*)(lds + (bufoff) + ldsw + _i * 8192), 16, 0, 0); } while (0)
; #define PG8_LDA(dst, b, h) do { _Pragma("unroll") for (int m = 0; m < 4; ++m) _Pragma("unroll") for (int k = 0; k < 2; ++k) dst[m][k] = *(const LAS bf16x8*)(lds + PG8_SA(b, h) + aoff + m * 2048 + k * 1024); } while (0)
; #define PG8_LDB(dst, b, h) do { _Pragma("unroll") for (int n = 0; n < 2; ++n) _Pragma("unroll") for (int k = 0; k < 2; ++k) dst[n][k] = *(const LAS bf16x8*)(lds + PG8_SB(b, h) + boff + n * 2048 + k * 1024); } while (0)
; #define PG8_MMA(ai, bj, At, Bt) do { __builtin_amdgcn_s_setprio(1); _Pragma("unroll") for (int m = 0; m < 4; ++m) _Pragma("unroll") for (int n = 0; n < 2; ++n) _Pragma("unroll") for (int k = 0; k < 2; ++k) \
;         acc[ai][bj][m][n] = __builtin_amdgcn_mfma_f32_16x16x32_bf16(Bt[n][k], At[m][k], acc[ai][bj][m][n], 0, 0, 0); __builtin_amdgcn_s_setprio(0); } while (0)
; #define PG8_WAIT_V(n) asm volatile("s_waitcnt vmcnt(" #n ")" ::: "memory")
; #define PG8_WAIT_L(n) asm volatile("s_waitcnt lgkmcnt(" #n ")" ::: "memory")
; #define PG8_BAR __builtin_amdgcn_s_barrier()
; #define PG8_SCHED __builtin_amdgcn_sched_barrier(0)
; template <class Epi, bool ALIGN_EPI = true, bool SP2 = true>
; DI void gemm_phase(LAS unsigned char* lds, const Gemm g, const StaticOrder& S, const Epi& E) {
;     ...
;             PG8_WAIT_V(8); PG8_WAIT_L(0); PG8_BAR; PG8_MMA(1, 0, At, B0); PG8_MMA(1, 1, At, B1); PG8_BAR; PG8_SCHED;
;             PG8_LDB(B0, 1, 0); PG8_LDB(B1, 1, 1); PG8_SCHED; PG8_LDA(At, 1, 0); PG8_STAGE(PG8_SA(0, 1), a2 + hstepA, voffA);
;             PG8_WAIT_V(8); PG8_WAIT_L(0); PG8_BAR; PG8_MMA(0, 0, At, B0); PG8_MMA(0, 1, At, B1); PG8_BAR; PG8_SCHED;
	s_waitcnt lgkmcnt(0)
	v_mfma_f32_16x16x32_bf16 v[60:63], v[140:143], v[180:183], v[60:63]
	v_mfma_f32_16x16x32_bf16 v[56:59], v[156:159], v[180:183], v[56:59]
	v_mfma_f32_16x16x32_bf16 v[52:55], v[140:143], v[188:191], v[52:55]
	v_mfma_f32_16x16x32_bf16 v[48:51], v[156:159], v[188:191], v[48:51]
	v_mfma_f32_16x16x32_bf16 v[44:47], v[140:143], v[196:199], v[44:47]
	v_mfma_f32_16x16x32_bf16 v[36:39], v[156:159], v[196:199], v[36:39]
	v_mfma_f32_16x16x32_bf16 v[28:31], v[140:143], v[204:207], v[28:31]
	v_mfma_f32_16x16x32_bf16 v[16:19], v[156:159], v[204:207], v[16:19]
	v_mfma_f32_16x16x32_bf16 v[60:63], v[152:155], v[184:187], v[60:63]
	v_mfma_f32_16x16x32_bf16 v[56:59], v[160:163], v[184:187], v[56:59]
	v_mfma_f32_16x16x32_bf16 v[52:55], v[152:155], v[192:195], v[52:55]
	v_mfma_f32_16x16x32_bf16 v[48:51], v[160:163], v[192:195], v[48:51]
	v_mfma_f32_16x16x32_bf16 v[44:47], v[152:155], v[200:203], v[44:47]
	v_mfma_f32_16x16x32_bf16 v[36:39], v[160:163], v[200:203], v[36:39]
	v_mfma_f32_16x16x32_bf16 v[28:31], v[152:155], v[208:211], v[28:31]
	v_mfma_f32_16x16x32_bf16 v[16:19], v[160:163], v[208:211], v[16:19]
	v_mfma_f32_16x16x32_bf16 v[40:43], v[164:167], v[180:183], v[40:43]
	v_mfma_f32_16x16x32_bf16 v[32:35], v[172:175], v[180:183], v[32:35]
	v_mfma_f32_16x16x32_bf16 v[24:27], v[164:167], v[188:191], v[24:27]
	v_mfma_f32_16x16x32_bf16 v[20:23], v[172:175], v[188:191], v[20:23]
	v_mfma_f32_16x16x32_bf16 v[12:15], v[164:167], v[196:199], v[12:15]
	v_mfma_f32_16x16x32_bf16 v[8:11], v[172:175], v[196:199], v[8:11]
	v_mfma_f32_16x16x32_bf16 v[4:7], v[164:167], v[204:207], v[4:7]
	v_mfma_f32_16x16x32_bf16 v[0:3], v[172:175], v[204:207], v[0:3]
	v_mfma_f32_16x16x32_bf16 v[40:43], v[168:171], v[184:187], v[40:43]
	v_mfma_f32_16x16x32_bf16 v[32:35], v[176:179], v[184:187], v[32:35]
	v_mfma_f32_16x16x32_bf16 v[24:27], v[168:171], v[192:195], v[24:27]
	v_mfma_f32_16x16x32_bf16 v[20:23], v[176:179], v[192:195], v[20:23]
	v_mfma_f32_16x16x32_bf16 v[12:15], v[168:171], v[200:203], v[12:15]
	v_mfma_f32_16x16x32_bf16 v[8:11], v[176:179], v[200:203], v[8:11]
	v_mfma_f32_16x16x32_bf16 v[4:7], v[168:171], v[208:211], v[4:7]
	v_mfma_f32_16x16x32_bf16 v[0:3], v[176:179], v[208:211], v[0:3]
	s_barrier
	s_add_i32 s60, 0, 0x18000
	s_add_i32 s61, 0, 0x1c000
	v_add_u32_e32 v160, s60, v147
	v_add_u32_e32 v176, s61, v147
	ds_read_b128 v[140:143], v160
	ds_read_b128 v[152:155], v160 offset:1024
	ds_read_b128 v[156:159], v160 offset:2048
	ds_read_b128 v[160:163], v160 offset:3072
	ds_read_b128 v[164:167], v176
	ds_read_b128 v[168:171], v176 offset:1024
	ds_read_b128 v[172:175], v176 offset:2048
	ds_read_b128 v[176:179], v176 offset:3072
	s_add_u32 s36, s36, 0x100000
	s_addc_u32 s37, s37, 0
	s_mov_b32 m0, s41
	v_lshl_add_u64 v[218:219], s[36:37], 0, v[128:129]
	ds_read_b128 v[180:183], v151 offset:32768
	ds_read_b128 v[184:187], v151 offset:33792
	ds_read_b128 v[188:191], v151 offset:34816
	ds_read_b128 v[192:195], v151 offset:35840
	ds_read_b128 v[196:199], v151 offset:36864
	ds_read_b128 v[200:203], v151 offset:37888
	ds_read_b128 v[204:207], v151 offset:38912
	ds_read_b128 v[208:211], v151 offset:39936
	global_load_lds_dwordx4 v[218:219], off
	s_mov_b32 m0, s42
	v_lshl_add_u64 v[218:219], s[36:37], 0, v[130:131]
	global_load_lds_dwordx4 v[218:219], off
	s_waitcnt vmcnt(8)
	s_waitcnt lgkmcnt(0)
	s_barrier
	s_waitcnt lgkmcnt(0)
	v_mfma_f32_16x16x32_bf16 v[124:127], v[140:143], v[180:183], v[124:127]
	v_mfma_f32_16x16x32_bf16 v[120:123], v[156:159], v[180:183], v[120:123]
	v_mfma_f32_16x16x32_bf16 v[116:119], v[140:143], v[188:191], v[116:119]
	v_mfma_f32_16x16x32_bf16 v[112:115], v[156:159], v[188:191], v[112:115]
	v_mfma_f32_16x16x32_bf16 v[108:111], v[140:143], v[196:199], v[108:111]
	v_mfma_f32_16x16x32_bf16 v[100:103], v[156:159], v[196:199], v[100:103]
	v_mfma_f32_16x16x32_bf16 v[92:95], v[140:143], v[204:207], v[92:95]
	v_mfma_f32_16x16x32_bf16 v[80:83], v[156:159], v[204:207], v[80:83]
	v_mfma_f32_16x16x32_bf16 v[124:127], v[152:155], v[184:187], v[124:127]
	v_mfma_f32_16x16x32_bf16 v[120:123], v[160:163], v[184:187], v[120:123]
	v_mfma_f32_16x16x32_bf16 v[116:119], v[152:155], v[192:195], v[116:119]
	v_mfma_f32_16x16x32_bf16 v[112:115], v[160:163], v[192:195], v[112:115]
	v_mfma_f32_16x16x32_bf16 v[108:111], v[152:155], v[200:203], v[108:111]
	v_mfma_f32_16x16x32_bf16 v[100:103], v[160:163], v[200:203], v[100:103]
	v_mfma_f32_16x16x32_bf16 v[92:95], v[152:155], v[208:211], v[92:95]
	v_mfma_f32_16x16x32_bf16 v[80:83], v[160:163], v[208:211], v[80:83]
	v_mfma_f32_16x16x32_bf16 v[104:107], v[164:167], v[180:183], v[104:107]
	v_mfma_f32_16x16x32_bf16 v[96:99], v[172:175], v[180:183], v[96:99]
	v_mfma_f32_16x16x32_bf16 v[88:91], v[164:167], v[188:191], v[88:91]
	v_mfma_f32_16x16x32_bf16 v[84:87], v[172:175], v[188:191], v[84:87]
	v_mfma_f32_16x16x32_bf16 v[76:79], v[164:167], v[196:199], v[76:79]
	v_mfma_f32_16x16x32_bf16 v[72:75], v[172:175], v[196:199], v[72:75]
	v_mfma_f32_16x16x32_bf16 v[68:71], v[164:167], v[204:207], v[68:71]
	v_mfma_f32_16x16x32_bf16 v[64:67], v[172:175], v[204:207], v[64:67]
	v_mfma_f32_16x16x32_bf16 v[104:107], v[168:171], v[184:187], v[104:107]
	v_mfma_f32_16x16x32_bf16 v[96:99], v[176:179], v[184:187], v[96:99]
	v_mfma_f32_16x16x32_bf16 v[88:91], v[168:171], v[192:195], v[88:91]
	v_mfma_f32_16x16x32_bf16 v[84:87], v[176:179], v[192:195], v[84:87]
	v_mfma_f32_16x16x32_bf16 v[76:79], v[168:171], v[200:203], v[76:79]
	v_mfma_f32_16x16x32_bf16 v[72:75], v[176:179], v[200:203], v[72:75]
	v_mfma_f32_16x16x32_bf16 v[68:71], v[168:171], v[208:211], v[68:71]
	v_mfma_f32_16x16x32_bf16 v[64:67], v[176:179], v[208:211], v[64:67]
	s_barrier
; #define PG8_STAGE(bufoff, gbase, voff) do { _Pragma("unroll") for (int _i = 0; _i < 2; ++_i) \
;         __builtin_amdgcn_global_load_lds((const unsigned*)((const char*)(gbase) + (voff)[_i]), (LAS unsigned*)(lds + (bufoff) + ldsw + _i * 8192), 16, 0, 0); } while (0)
; #define PG8_LDA(dst, b, h) do { _Pragma("unroll") for (int m = 0; m < 4; ++m) _Pragma("unroll") for (int k = 0; k < 2; ++k) dst[m][k] = *(const LAS bf16x8*)(lds + PG8_SA(b, h) + aoff + m * 2048 + k * 1024); } while (0)
; #define PG8_MMA(ai, bj, At, Bt) do { __builtin_amdgcn_s_setprio(1); _Pragma("unroll") for (int m = 0; m < 4; ++m) _Pragma("unroll") for (int n = 0; n < 2; ++n) _Pragma("unroll") for (int k = 0; k < 2; ++k) \
;         acc[ai][bj][m][n] = __builtin_amdgcn_mfma_f32_16x16x32_bf16(Bt[n][k], At[m][k], acc[ai][bj][m][n], 0, 0, 0); __builtin_amdgcn_s_setprio(0); } while (0)
; #define PG8_WAIT_V(n) asm volatile("s_waitcnt vmcnt(" #n ")" ::: "memory")
; #define PG8_WAIT_L(n) asm volatile("s_waitcnt lgkmcnt(" #n ")" ::: "memory")
; #define PG8_BAR __builtin_amdgcn_s_barrier()
; #define PG8_SCHED __builtin_amdgcn_sched_barrier(0)
; template <class Epi, bool ALIGN_EPI = true, bool SP2 = true>
; DI void gemm_phase(LAS unsigned char* lds, const Gemm g, const StaticOrder& S, const Epi& E) {
;     ...
;             PG8_LDA(At, 1, 1); PG8_STAGE(PG8_SB(1, 0), b3, voffB); PG8_STAGE(PG8_SB(1, 1), b3 + hstepB, voffB); PG8_STAGE(PG8_SA(1, 0), a3, voffA);
;             PG8_WAIT_V(8); PG8_WAIT_L(0); PG8_BAR; PG8_MMA(1, 0, At, B0); PG8_MMA(1, 1, At, B1); PG8_BAR; PG8_SCHED;
;     ...
;         if constexpr (ALIGN_EPI) { if (wr == 0) PG8_BAR; }
	s_add_i32 s36, s60, s39
	v_lshl_add_u64 v[144:145], v[144:145], 0, s[6:7]
	s_mov_b32 m0, s36
	ds_read_b128 v[180:183], v151 offset:49152
	ds_read_b128 v[184:187], v151 offset:50176
	ds_read_b128 v[188:191], v151 offset:51200
	ds_read_b128 v[192:195], v151 offset:52224
	ds_read_b128 v[196:199], v151 offset:53248
	ds_read_b128 v[200:203], v151 offset:54272
	ds_read_b128 v[204:207], v151 offset:55296
	ds_read_b128 v[208:211], v151 offset:56320
	global_load_lds_dwordx4 v[144:145], off
	s_add_i32 m0, s36, 0x2000
	s_add_u32 s34, s34, 0x100080
	v_lshl_add_u64 v[144:145], v[212:213], 0, s[6:7]
	s_addc_u32 s35, s35, 0
	s_add_i32 s36, s61, s39
	global_load_lds_dwordx4 v[144:145], off
	s_mov_b32 m0, s36
	v_lshl_add_u64 v[144:145], s[34:35], 0, v[128:129]
	global_load_lds_dwordx4 v[144:145], off
	s_add_i32 m0, s36, 0x2000
	v_lshl_add_u64 v[144:145], s[34:35], 0, v[130:131]
	global_load_lds_dwordx4 v[144:145], off
	s_mov_b32 m0, s44
	v_lshl_add_u64 v[144:145], v[214:215], 0, s[6:7]
	global_load_lds_dwordx4 v[144:145], off
	s_mov_b32 m0, s45
	v_lshl_add_u64 v[144:145], v[216:217], 0, s[6:7]
	global_load_lds_dwordx4 v[144:145], off
	s_waitcnt vmcnt(8)
	s_waitcnt lgkmcnt(0)
	s_barrier
	s_waitcnt lgkmcnt(0)
	v_mfma_f32_16x16x32_bf16 v[60:63], v[140:143], v[180:183], v[60:63]
	v_mfma_f32_16x16x32_bf16 v[56:59], v[156:159], v[180:183], v[56:59]
	v_mfma_f32_16x16x32_bf16 v[52:55], v[140:143], v[188:191], v[52:55]
	v_mfma_f32_16x16x32_bf16 v[48:51], v[156:159], v[188:191], v[48:51]
	v_mfma_f32_16x16x32_bf16 v[44:47], v[140:143], v[196:199], v[44:47]
	v_mfma_f32_16x16x32_bf16 v[36:39], v[156:159], v[196:199], v[36:39]
	v_mfma_f32_16x16x32_bf16 v[28:31], v[140:143], v[204:207], v[28:31]
	v_mfma_f32_16x16x32_bf16 v[16:19], v[156:159], v[204:207], v[16:19]
	v_mfma_f32_16x16x32_bf16 v[60:63], v[152:155], v[184:187], v[60:63]
	v_mfma_f32_16x16x32_bf16 v[56:59], v[160:163], v[184:187], v[56:59]
	v_mfma_f32_16x16x32_bf16 v[52:55], v[152:155], v[192:195], v[52:55]
	v_mfma_f32_16x16x32_bf16 v[48:51], v[160:163], v[192:195], v[48:51]
	v_mfma_f32_16x16x32_bf16 v[44:47], v[152:155], v[200:203], v[44:47]
	v_mfma_f32_16x16x32_bf16 v[36:39], v[160:163], v[200:203], v[36:39]
	v_mfma_f32_16x16x32_bf16 v[28:31], v[152:155], v[208:211], v[28:31]
	v_mfma_f32_16x16x32_bf16 v[16:19], v[160:163], v[208:211], v[16:19]
	v_mfma_f32_16x16x32_bf16 v[40:43], v[164:167], v[180:183], v[40:43]
	v_mfma_f32_16x16x32_bf16 v[32:35], v[172:175], v[180:183], v[32:35]
	v_mfma_f32_16x16x32_bf16 v[24:27], v[164:167], v[188:191], v[24:27]
	v_mfma_f32_16x16x32_bf16 v[20:23], v[172:175], v[188:191], v[20:23]
	v_mfma_f32_16x16x32_bf16 v[12:15], v[164:167], v[196:199], v[12:15]
	v_mfma_f32_16x16x32_bf16 v[8:11], v[172:175], v[196:199], v[8:11]
	v_mfma_f32_16x16x32_bf16 v[4:7], v[164:167], v[204:207], v[4:7]
	v_mfma_f32_16x16x32_bf16 v[0:3], v[172:175], v[204:207], v[0:3]
	v_mfma_f32_16x16x32_bf16 v[40:43], v[168:171], v[184:187], v[40:43]
	v_mfma_f32_16x16x32_bf16 v[32:35], v[176:179], v[184:187], v[32:35]
	v_mfma_f32_16x16x32_bf16 v[24:27], v[168:171], v[192:195], v[24:27]
	v_mfma_f32_16x16x32_bf16 v[20:23], v[176:179], v[192:195], v[20:23]
	v_mfma_f32_16x16x32_bf16 v[12:15], v[168:171], v[200:203], v[12:15]
	v_mfma_f32_16x16x32_bf16 v[8:11], v[176:179], v[200:203], v[8:11]
	v_mfma_f32_16x16x32_bf16 v[4:7], v[168:171], v[208:211], v[4:7]
	v_mfma_f32_16x16x32_bf16 v[0:3], v[176:179], v[208:211], v[0:3]
	s_barrier
	s_add_i32 s59, s59, 2
	s_add_u32 s30, s30, 0x100
	s_addc_u32 s31, s31, 0
	s_add_u32 s56, s56, 0x100
	s_addc_u32 s57, s57, 0
	s_cmp_gt_u32 s59, 61
	s_cbranch_scc0 .LBB0_839
	s_and_b64 vcc, exec, s[8:9]
	s_cbranch_vccz .LBB0_842
	s_barrier
